# attention loop unrolled 4x: K/V LDS slots as immediate offsets, no per-tile address updates; V ring 4 slots
# speedup vs baseline: 1.0235x; 1.0063x over previous
.LBB0_1332:
	v_and_b32_e32 v85, 64, v193
	ds_read_b128 v[72:75], v144 offset:49152
	ds_read_b128 v[76:79], v144 offset:53248
	ds_read_b128 v[80:83], v145 offset:49152
	v_xor_b32_e32 v84, 32, v193
	v_add_u32_e32 v85, 64, v85
	v_cmp_lt_i32_e32 vcc, v84, v85
	s_waitcnt lgkmcnt(2)
	v_mfma_f32_32x32x16_bf16 v[48:63], v[72:75], v[68:71], v[48:63]
	s_add_i32 s97, s97, s91
	v_cndmask_b32_e32 v84, v193, v84, vcc
	v_lshlrev_b32_e32 v72, 2, v84
	ds_bpermute_b32 v88, v72, v200
	ds_read_b128 v[72:75], v144 offset:57344
	ds_read_b128 v[84:87], v145 offset:53248
	s_add_i32 s96, s96, 1
	s_cmp_eq_u32 s96, 4
	s_waitcnt lgkmcnt(4)
	v_mfma_f32_32x32x16_bf16 v[32:47], v[76:79], v[68:71], v[32:47]
	s_waitcnt lgkmcnt(2)
	v_add_f32_e32 v96, v200, v88
	ds_read_b128 v[76:79], v145 offset:57344
	ds_read_b128 v[88:91], v144 offset:61440
	ds_read_b128 v[92:95], v145 offset:61440
	v_div_scale_f32 v97, s[0:1], v96, v96, 1.0
	v_rcp_f32_e32 v98, v97
	s_nop 0
	v_fma_f32 v99, -v97, v98, 1.0
	s_waitcnt lgkmcnt(4)
	v_mfma_f32_32x32x16_bf16 v[16:31], v[72:75], v[68:71], v[16:31]
	v_fmac_f32_e32 v98, v99, v98
	v_div_scale_f32 v72, vcc, 1.0, v96, 1.0
	v_mul_f32_e32 v73, v72, v98
	v_fma_f32 v74, -v97, v73, v72
	v_fmac_f32_e32 v73, v74, v98
	v_fma_f32 v72, -v97, v73, v72
	s_waitcnt lgkmcnt(1)
	v_mfma_f32_32x32x16_bf16 v[0:15], v[88:91], v[68:71], v[0:15]
	v_mov_b32_e32 v69, v191
	v_div_fmas_f32 v68, v72, v98, v73
	v_and_or_b32 v70, v69, 31, s97
	v_ashrrev_i32_e32 v71, 31, v70
	v_div_fixup_f32 v68, v68, v96, 1.0
	v_lshlrev_b64 v[70:71], 11, v[70:71]
	v_mfma_f32_32x32x16_bf16 v[48:63], v[80:83], v[64:67], v[48:63]
	v_lshrrev_b32_e32 v69, 2, v69
	v_lshl_add_u64 v[70:71], s[70:71], 0, v[70:71]
	v_and_b32_e32 v180, 8, v69
	v_lshl_add_u64 v[70:71], v[70:71], 0, v[180:181]
	v_mfma_f32_32x32x16_bf16 v[32:47], v[84:87], v[64:67], v[32:47]
	s_nop 6
	v_mul_f32_e64 v48, v48, v68
	v_mul_f32_e64 v49, v49, v68
	v_mul_f32_e64 v50, v50, v68
	v_mul_f32_e64 v51, v51, v68
	v_cvt_pk_bf16_f32 v48, v48, v49
	v_cvt_pk_bf16_f32 v49, v50, v51
	global_store_dwordx2 v[70:71], v[48:49], off
	v_pk_mul_f32 v[48:49], v[52:53], v[68:69] op_sel_hi:[1,0]
	v_pk_mul_f32 v[50:51], v[54:55], v[68:69] op_sel_hi:[1,0]
	v_mfma_f32_32x32x16_bf16 v[16:31], v[76:79], v[64:67], v[16:31]
	v_mul_f32_e64 v32, v32, v68
	v_mul_f32_e64 v33, v33, v68
	v_mul_f32_e64 v34, v34, v68
	v_mul_f32_e64 v35, v35, v68
	v_cvt_pk_bf16_f32 v32, v32, v33
	v_cvt_pk_bf16_f32 v33, v34, v35
	global_store_dwordx2 v[70:71], v[32:33], off offset:64
	v_pk_mul_f32 v[32:33], v[36:37], v[68:69] op_sel_hi:[1,0]
	v_pk_mul_f32 v[34:35], v[38:39], v[68:69] op_sel_hi:[1,0]
	s_waitcnt lgkmcnt(0)
	v_mfma_f32_32x32x16_bf16 v[0:15], v[92:95], v[64:67], v[0:15]
	s_nop 0
	v_mul_f32_e64 v16, v16, v68
	v_mul_f32_e64 v17, v17, v68
	v_mul_f32_e64 v18, v18, v68
	v_mul_f32_e64 v19, v19, v68
	v_cvt_pk_bf16_f32 v16, v16, v17
	v_cvt_pk_bf16_f32 v17, v18, v19
	global_store_dwordx2 v[70:71], v[16:17], off offset:128
	v_pk_mul_f32 v[16:17], v[20:21], v[68:69] op_sel_hi:[1,0]
	v_pk_mul_f32 v[18:19], v[22:23], v[68:69] op_sel_hi:[1,0]
	s_nop 1
	v_pk_mul_f32 v[0:1], v[0:1], v[68:69] op_sel_hi:[1,0]
	v_pk_mul_f32 v[2:3], v[2:3], v[68:69] op_sel_hi:[1,0]
	v_cvt_pk_bf16_f32 v0, v0, v1
	v_cvt_pk_bf16_f32 v1, v2, v3
	global_store_dwordx2 v[70:71], v[0:1], off offset:192
	v_pk_mul_f32 v[0:1], v[4:5], v[68:69] op_sel_hi:[1,0]
	v_pk_mul_f32 v[2:3], v[6:7], v[68:69] op_sel_hi:[1,0]
	v_cvt_pk_bf16_f32 v48, v48, v49
	v_cvt_pk_bf16_f32 v49, v50, v51
	v_cvt_pk_bf16_f32 v32, v32, v33
	v_cvt_pk_bf16_f32 v33, v34, v35
	v_cvt_pk_bf16_f32 v16, v16, v17
	v_cvt_pk_bf16_f32 v17, v18, v19
	v_cvt_pk_bf16_f32 v0, v0, v1
	v_cvt_pk_bf16_f32 v1, v2, v3
	global_store_dwordx2 v[70:71], v[48:49], off offset:16
	v_pk_mul_f32 v[48:49], v[56:57], v[68:69] op_sel_hi:[1,0]
	v_pk_mul_f32 v[50:51], v[58:59], v[68:69] op_sel_hi:[1,0]
	global_store_dwordx2 v[70:71], v[32:33], off offset:80
	v_pk_mul_f32 v[32:33], v[40:41], v[68:69] op_sel_hi:[1,0]
	v_pk_mul_f32 v[34:35], v[42:43], v[68:69] op_sel_hi:[1,0]
	global_store_dwordx2 v[70:71], v[16:17], off offset:144
	v_pk_mul_f32 v[16:17], v[24:25], v[68:69] op_sel_hi:[1,0]
	v_pk_mul_f32 v[18:19], v[26:27], v[68:69] op_sel_hi:[1,0]
	global_store_dwordx2 v[70:71], v[0:1], off offset:208
	v_pk_mul_f32 v[0:1], v[8:9], v[68:69] op_sel_hi:[1,0]
	v_pk_mul_f32 v[2:3], v[10:11], v[68:69] op_sel_hi:[1,0]
	v_cvt_pk_bf16_f32 v48, v48, v49
	v_cvt_pk_bf16_f32 v49, v50, v51
	v_cvt_pk_bf16_f32 v32, v32, v33
	v_cvt_pk_bf16_f32 v33, v34, v35
	v_cvt_pk_bf16_f32 v16, v16, v17
	v_cvt_pk_bf16_f32 v17, v18, v19
	v_cvt_pk_bf16_f32 v0, v0, v1
	v_cvt_pk_bf16_f32 v1, v2, v3
	global_store_dwordx2 v[70:71], v[48:49], off offset:32
	v_pk_mul_f32 v[48:49], v[60:61], v[68:69] op_sel_hi:[1,0]
	v_pk_mul_f32 v[50:51], v[62:63], v[68:69] op_sel_hi:[1,0]
	global_store_dwordx2 v[70:71], v[32:33], off offset:96
	v_pk_mul_f32 v[32:33], v[44:45], v[68:69] op_sel_hi:[1,0]
	v_pk_mul_f32 v[34:35], v[46:47], v[68:69] op_sel_hi:[1,0]
	global_store_dwordx2 v[70:71], v[16:17], off offset:160
	v_pk_mul_f32 v[16:17], v[28:29], v[68:69] op_sel_hi:[1,0]
	v_pk_mul_f32 v[18:19], v[30:31], v[68:69] op_sel_hi:[1,0]
	global_store_dwordx2 v[70:71], v[0:1], off offset:224
	v_pk_mul_f32 v[0:1], v[12:13], v[68:69] op_sel_hi:[1,0]
	v_pk_mul_f32 v[2:3], v[14:15], v[68:69] op_sel_hi:[1,0]
	v_cvt_pk_bf16_f32 v48, v48, v49
	v_cvt_pk_bf16_f32 v49, v50, v51
	v_cvt_pk_bf16_f32 v32, v32, v33
	v_cvt_pk_bf16_f32 v33, v34, v35
	v_cvt_pk_bf16_f32 v16, v16, v17
	v_cvt_pk_bf16_f32 v17, v18, v19
	v_cvt_pk_bf16_f32 v0, v0, v1
	v_cvt_pk_bf16_f32 v1, v2, v3
	global_store_dwordx2 v[70:71], v[48:49], off offset:48
	global_store_dwordx2 v[70:71], v[32:33], off offset:112
	global_store_dwordx2 v[70:71], v[16:17], off offset:176
	global_store_dwordx2 v[70:71], v[0:1], off offset:240
	s_barrier
	s_cbranch_scc1 .LBB0_1329

.LBB0_1338:
	v_mov_b32_e32 v54, v191
	s_lshl_b32 s97, s4, 8
	s_add_i32 s97, s97, s79
	v_and_b32_e32 v48, 31, v54
	v_or_b32_e32 v0, s97, v48
	v_ashrrev_i32_e32 v50, 3, v54
	v_and_b32_e32 v56, 7, v54
	v_bfe_u32 v49, v54, 5, 1
	v_add_u32_e32 v0, s91, v0
	s_movk_i32 s0, 0xc00
	v_ashrrev_i32_e32 v51, 4, v54
	v_and_b32_e32 v55, 15, v54
	v_add_u32_e32 v9, s91, v50
	v_lshlrev_b32_e32 v52, 3, v56
	v_and_b32_e32 v172, 7, v51
	v_lshlrev_b32_e32 v172, 3, v172
	v_xor_b32_e32 v52, v172, v52
	v_ashrrev_i32_e32 v1, 31, v0
	v_mad_i64_i32 v[2:3], s[0:1], v0, s0, v[182:183]
	v_lshlrev_b32_e32 v180, 4, v49
	v_add_lshl_u32 v8, v51, s91, 10
	v_lshlrev_b32_e32 v53, 3, v55
	v_and_b32_e32 v172, 15, v51
	v_lshlrev_b32_e32 v172, 3, v172
	v_xor_b32_e32 v53, v172, v53
	v_lshl_or_b32 v10, v9, 6, v52
	v_add_lshl_u32 v9, v50, s92, 15
	v_lshl_add_u64 v[24:25], v[2:3], 0, v[180:181]
	v_lshlrev_b64 v[0:1], 7, v[0:1]
	v_or3_b32 v8, v8, v53, s92
	v_or3_b32 v12, v9, s91, v52
	v_add_lshl_u32 v234, v50, s92, 11
	v_add_u32_e32 v12, v12, v234
	v_mov_b32_e32 v9, v181
	global_load_dwordx4 v[96:99], v[24:25], off
	global_load_dwordx4 v[100:103], v[24:25], off offset:32
	global_load_dwordx4 v[104:107], v[24:25], off offset:64
	global_load_dwordx4 v[108:111], v[24:25], off offset:96
	global_load_dwordx4 v[112:115], v[24:25], off offset:128
	global_load_dwordx4 v[116:119], v[24:25], off offset:160
	global_load_dwordx4 v[120:123], v[24:25], off offset:192
	global_load_dwordx4 v[124:127], v[24:25], off offset:224
	v_lshl_add_u64 v[2:3], s[62:63], 0, v[0:1]
	v_lshlrev_b32_e32 v4, 5, v49
	v_mov_b32_e32 v5, v181
	v_lshl_add_u64 v[14:15], v[8:9], 1, s[64:65]
	v_add_u32_e32 v8, 0x8000, v8
	v_lshl_add_u64 v[28:29], v[2:3], 0, v[4:5]
	v_lshl_add_u64 v[0:1], s[66:67], 0, v[0:1]
	v_lshl_add_u64 v[8:9], v[8:9], 1, s[64:65]
	v_mov_b32_e32 v11, v181
	v_lshl_add_u64 v[44:45], v[0:1], 0, v[4:5]
	global_load_dwordx4 v[0:3], v[28:29], off offset:16
	global_load_dwordx4 v[4:7], v[28:29], off
	s_and_b32 s5, s97, 0xe0
	s_lshl_b32 s5, s5, 5
	s_mov_b32 m0, s5
	s_nop 0
	global_load_lds_dwordx4 v[14:15], off
	s_add_i32 m0, s5, 0x2000
	s_nop 0
	global_load_lds_dwordx4 v[8:9], off
	v_lshl_add_u64 v[8:9], v[10:11], 1, s[60:61]
	v_mov_b32_e32 v13, v181
	v_lshl_add_u64 v[10:11], v[12:13], 1, s[68:69]
	s_add_i32 m0, s5, 0x8000
	s_nop 0
	global_load_lds_dwordx4 v[8:9], off
	s_add_i32 m0, s5, 0xc000
	s_nop 0
	global_load_lds_dwordx4 v[10:11], off
	v_add_u32_e32 v8, 0x220000, v12
	v_mov_b32_e32 v9, v181
	v_lshl_add_u64 v[8:9], v[8:9], 1, s[68:69]
	s_add_i32 m0, s5, 0xe000
	s_nop 0
	global_load_lds_dwordx4 v[8:9], off
	s_nop 0
	global_load_dwordx4 v[8:11], v[44:45], off offset:16
	global_load_dwordx4 v[20:23], v[44:45], off
	global_load_dwordx4 v[12:15], v[24:25], off offset:256
	global_load_dwordx4 v[32:35], v[24:25], off offset:288
	global_load_dwordx4 v[16:19], v[24:25], off offset:320
	global_load_dwordx4 v[36:39], v[24:25], off offset:352
	s_nop 0
	global_load_dwordx4 v[24:27], v[28:29], off offset:80
	global_load_dwordx4 v[40:43], v[28:29], off offset:64
	s_nop 0
	global_load_dwordx4 v[28:31], v[44:45], off offset:80
	s_nop 0
	global_load_dwordx4 v[44:47], v[44:45], off offset:64
	v_lshlrev_b32_e32 v57, 3, v54
	v_mul_lo_u32 v58, v51, s82
	v_lshlrev_b32_e32 v54, 4, v56
	v_mul_lo_u32 v56, v50, s83
	v_lshl_add_u32 v194, v55, 4, v58
	v_and_b32_e32 v55, 0x60, v54
	v_and_b32_e32 v57, 8, v57
	v_mad_u64_u32 v[184:185], s[0:1], v50, s82, v[54:55]
	v_add_u32_e32 v54, 0, v56
	v_add3_u32 v185, v54, v57, v55
	v_add_u32_e32 v56, 0, v194
	v_add_u32_e32 v54, 0xc800, v185
	v_add_u32_e32 v58, 0, v184
	v_add_u32_e32 v55, 0xe800, v185
	s_cmp_lt_i32 s4, 0
	s_mov_b32 s52, 0
	s_waitcnt vmcnt(0)
	v_mad_u32_u24 v54, v48, s83, 0
	v_add_u32_e32 v195, v54, v180
	v_and_b32_e32 v172, 0x13, v48
	v_and_b32_e32 v175, 4, v48
	v_lshl_or_b32 v172, v175, 1, v172
	v_and_b32_e32 v175, 8, v48
	v_lshrrev_b32_e32 v175, 1, v175
	v_or_b32_e32 v172, v172, v175
	v_and_b32_e32 v175, 15, v172
	v_xor_b32_e32 v175, v175, v49
	v_lshlrev_b32_e32 v175, 4, v175
	v_lshl_or_b32 v128, v172, 8, v175
	v_xor_b32_e32 v129, 0x20, v128
	v_xor_b32_e32 v130, 0x40, v128
	v_xor_b32_e32 v131, 0x60, v128
	v_xor_b32_e32 v132, 0x80, v128
	v_xor_b32_e32 v133, 0xa0, v128
	v_xor_b32_e32 v134, 0xc0, v128
	v_xor_b32_e32 v135, 0xe0, v128
	v_bfe_u32 v175, v172, 1, 3
	v_xor_b32_e32 v175, v175, v49
	v_lshlrev_b32_e32 v175, 4, v175
	v_lshl_or_b32 v136, v172, 7, v175
	v_add_u32_e32 v136, 0x8000, v136
	v_xor_b32_e32 v137, 0x20, v136
	v_xor_b32_e32 v138, 0x40, v136
	v_xor_b32_e32 v139, 0x60, v136
	v_bfe_u32 v175, v48, 1, 3
	v_xor_b32_e32 v175, v175, v49
	v_lshlrev_b32_e32 v175, 4, v175
	v_lshl_or_b32 v140, v48, 7, v175
	v_add_u32_e32 v140, 0xc000, v140
	v_xor_b32_e32 v141, 32, v140
	v_xor_b32_e32 v144, 64, v140
	v_xor_b32_e32 v145, 64, v141
	s_waitcnt lgkmcnt(0)
	s_barrier
	s_cbranch_scc1 .LBB0_1331
	v_lshlrev_b32_e32 v55, 8, v48
	v_add3_u32 v196, v54, v55, v180
	v_and_b32_e32 v55, 0xffff0000, v36
	v_lshlrev_b32_e32 v54, 16, v36
	v_and_b32_e32 v57, 0xffff0000, v32
	v_lshlrev_b32_e32 v56, 16, v32
	v_pk_mul_f32 v[58:59], v[44:45], v[56:57]
	v_pk_mul_f32 v[44:45], v[44:45], v[54:55]
	v_pk_fma_f32 v[58:59], v[40:41], v[54:55], v[58:59]
	v_pk_fma_f32 v[40:41], v[40:41], v[56:57], v[44:45] neg_lo:[0,0,1] neg_hi:[0,0,1]
	v_lshlrev_b32_e32 v36, 16, v33
	v_cvt_pk_bf16_f32 v152, v40, v41
	v_and_b32_e32 v41, 0xffff0000, v37
	v_lshlrev_b32_e32 v40, 16, v37
	v_and_b32_e32 v37, 0xffff0000, v33
	v_pk_mul_f32 v[32:33], v[46:47], v[36:37]
	s_lshl_b32 s53, s4, 2
	v_pk_fma_f32 v[32:33], v[42:43], v[40:41], v[32:33]
	v_mov_b32_e32 v200, 0
	v_cvt_pk_bf16_f32 v149, v32, v33
	v_pk_mul_f32 v[32:33], v[46:47], v[40:41]
	s_add_i32 s53, s53, 4
	v_pk_fma_f32 v[32:33], v[42:43], v[36:37], v[32:33] neg_lo:[0,0,1] neg_hi:[0,0,1]
	v_and_b32_e32 v37, 0xffff0000, v34
	v_cvt_pk_bf16_f32 v153, v32, v33
	v_and_b32_e32 v33, 0xffff0000, v38
	v_lshlrev_b32_e32 v32, 16, v38
	v_lshlrev_b32_e32 v36, 16, v34
	v_pk_mul_f32 v[40:41], v[28:29], v[36:37]
	v_pk_mul_f32 v[28:29], v[28:29], v[32:33]
	v_pk_fma_f32 v[40:41], v[24:25], v[32:33], v[40:41]
	v_pk_fma_f32 v[24:25], v[24:25], v[36:37], v[28:29] neg_lo:[0,0,1] neg_hi:[0,0,1]
	v_and_b32_e32 v29, 0xffff0000, v35
	v_lshlrev_b32_e32 v28, 16, v35
	v_cvt_pk_bf16_f32 v154, v24, v25
	v_and_b32_e32 v25, 0xffff0000, v39
	v_lshlrev_b32_e32 v24, 16, v39
	v_pk_mul_f32 v[32:33], v[30:31], v[28:29]
	v_cvt_pk_bf16_f32 v148, v58, v59
	v_pk_fma_f32 v[32:33], v[26:27], v[24:25], v[32:33]
	v_pk_mul_f32 v[24:25], v[30:31], v[24:25]
	v_cvt_pk_bf16_f32 v150, v40, v41
	v_pk_fma_f32 v[24:25], v[26:27], v[28:29], v[24:25] neg_lo:[0,0,1] neg_hi:[0,0,1]
	v_and_b32_e32 v27, 0xffff0000, v12
	v_cvt_pk_bf16_f32 v155, v24, v25
	v_and_b32_e32 v25, 0xffff0000, v16
	v_lshlrev_b32_e32 v24, 16, v16
	v_lshlrev_b32_e32 v26, 16, v12
	v_pk_mul_f32 v[28:29], v[20:21], v[26:27]
	v_pk_mul_f32 v[20:21], v[20:21], v[24:25]
	v_pk_fma_f32 v[28:29], v[4:5], v[24:25], v[28:29]
	v_pk_fma_f32 v[4:5], v[4:5], v[26:27], v[20:21] neg_lo:[0,0,1] neg_hi:[0,0,1]
	v_lshlrev_b32_e32 v16, 16, v13
	v_cvt_pk_bf16_f32 v160, v4, v5
	v_and_b32_e32 v5, 0xffff0000, v17
	v_lshlrev_b32_e32 v4, 16, v17
	v_and_b32_e32 v17, 0xffff0000, v13
	v_pk_mul_f32 v[12:13], v[22:23], v[16:17]
	v_cvt_pk_bf16_f32 v151, v32, v33
	v_pk_fma_f32 v[12:13], v[6:7], v[4:5], v[12:13]
	v_pk_mul_f32 v[4:5], v[22:23], v[4:5]
	v_cvt_pk_bf16_f32 v157, v12, v13
	v_pk_fma_f32 v[4:5], v[6:7], v[16:17], v[4:5] neg_lo:[0,0,1] neg_hi:[0,0,1]
	v_and_b32_e32 v7, 0xffff0000, v14
	v_lshlrev_b32_e32 v6, 16, v14
	v_cvt_pk_bf16_f32 v161, v4, v5
	v_and_b32_e32 v5, 0xffff0000, v18
	v_lshlrev_b32_e32 v4, 16, v18
	v_pk_mul_f32 v[12:13], v[8:9], v[6:7]
	v_cvt_pk_bf16_f32 v156, v28, v29
	v_pk_fma_f32 v[12:13], v[0:1], v[4:5], v[12:13]
	v_pk_mul_f32 v[4:5], v[8:9], v[4:5]
	v_cvt_pk_bf16_f32 v158, v12, v13
	v_pk_fma_f32 v[0:1], v[0:1], v[6:7], v[4:5] neg_lo:[0,0,1] neg_hi:[0,0,1]
	v_and_b32_e32 v5, 0xffff0000, v15
	v_lshlrev_b32_e32 v4, 16, v15
	v_cvt_pk_bf16_f32 v162, v0, v1
	v_and_b32_e32 v1, 0xffff0000, v19
	v_lshlrev_b32_e32 v0, 16, v19
	v_pk_mul_f32 v[6:7], v[10:11], v[4:5]
	v_mov_b32_e32 v199, 0xf149f2ca
	v_pk_fma_f32 v[6:7], v[2:3], v[0:1], v[6:7]
	v_pk_mul_f32 v[0:1], v[10:11], v[0:1]
	v_cvt_pk_bf16_f32 v159, v6, v7
	v_pk_fma_f32 v[0:1], v[2:3], v[4:5], v[0:1] neg_lo:[0,0,1] neg_hi:[0,0,1]
	s_mov_b32 s33, 63
	v_cvt_pk_bf16_f32 v163, v0, v1
	v_lshlrev_b32_e32 v1, 10, v51
	v_lshlrev_b32_e32 v0, 3, v49
	v_add3_u32 v186, s93, v1, v53
	v_add_u32_e32 v1, s97, v48
	v_sub_u32_e32 v197, v1, v0
	v_lshlrev_b32_e32 v0, 6, v50
	v_add3_u32 v188, s94, v0, v52
	v_lshlrev_b32_e32 v0, 15, v50
	v_add3_u32 v198, s95, v0, v52
	v_add_lshl_u32 v234, v50, s92, 11
	v_add_u32_e32 v198, v198, v234
	v_mov_b32_e32 v64, 0
	v_mov_b32_e32 v65, 0
	v_mov_b32_e32 v66, 0
	v_mov_b32_e32 v67, 0
	v_mov_b32_e32 v68, 0
	v_mov_b32_e32 v69, 0
	v_mov_b32_e32 v70, 0
	v_mov_b32_e32 v71, 0
	s_mov_b32 s0, 0
	v_mov_b32_e32 v0, 0
	v_mov_b32_e32 v1, v200
	v_mov_b32_e32 v2, v200
	v_mov_b32_e32 v3, v200
	v_mov_b32_e32 v4, v200
	v_mov_b32_e32 v5, v200
	v_mov_b32_e32 v6, v200
	v_mov_b32_e32 v7, v200
	v_mov_b32_e32 v8, v200
	v_mov_b32_e32 v9, v200
	v_mov_b32_e32 v10, v200
	v_mov_b32_e32 v11, v200
	v_mov_b32_e32 v12, v200
	v_mov_b32_e32 v13, v200
	v_mov_b32_e32 v14, v200
	v_mov_b32_e32 v15, v200
	v_mov_b32_e32 v16, 0
	v_mov_b32_e32 v17, v200
	v_mov_b32_e32 v18, v200
	v_mov_b32_e32 v19, v200
	v_mov_b32_e32 v20, v200
	v_mov_b32_e32 v21, v200
	v_mov_b32_e32 v22, v200
	v_mov_b32_e32 v23, v200
	v_mov_b32_e32 v24, v200
	v_mov_b32_e32 v25, v200
	v_mov_b32_e32 v26, v200
	v_mov_b32_e32 v27, v200
	v_mov_b32_e32 v28, v200
	v_mov_b32_e32 v29, v200
	v_mov_b32_e32 v30, v200
	v_mov_b32_e32 v31, v200
	v_mov_b32_e32 v32, 0
	v_mov_b32_e32 v33, v200
	v_mov_b32_e32 v34, v200
	v_mov_b32_e32 v35, v200
	v_mov_b32_e32 v36, v200
	v_mov_b32_e32 v37, v200
	v_mov_b32_e32 v38, v200
	v_mov_b32_e32 v39, v200
	v_mov_b32_e32 v40, v200
	v_mov_b32_e32 v41, v200
	v_mov_b32_e32 v42, v200
	v_mov_b32_e32 v43, v200
	v_mov_b32_e32 v44, v200
	v_mov_b32_e32 v45, v200
	v_mov_b32_e32 v46, v200
	v_mov_b32_e32 v47, v200
	v_mov_b32_e32 v48, 0
	v_mov_b32_e32 v49, v200
	v_mov_b32_e32 v50, v200
	v_mov_b32_e32 v51, v200
	v_mov_b32_e32 v52, v200
	v_mov_b32_e32 v53, v200
	v_mov_b32_e32 v54, v200
	v_mov_b32_e32 v55, v200
	v_mov_b32_e32 v56, v200
	v_mov_b32_e32 v57, v200
	v_mov_b32_e32 v58, v200
	v_mov_b32_e32 v59, v200
	v_mov_b32_e32 v60, v200
	v_mov_b32_e32 v61, v200
	v_mov_b32_e32 v62, v200
	v_mov_b32_e32 v63, v200
	s_mov_b32 s55, 0
	s_and_b32 s52, s97, 0xe0
	s_lshl_b32 s52, s52, 5
	v_xor_b32_e32 v246, 32, v193
	v_lshlrev_b32_e32 v246, 2, v246
	v_mov_b32_e32 v64, 0xff61b1e6
	v_mov_b32_e32 v65, v64
	v_mov_b32_e32 v66, v64
	v_mov_b32_e32 v67, v64
	v_mov_b32_e32 v68, v64
	v_mov_b32_e32 v69, v64
	v_mov_b32_e32 v70, v64
	v_mov_b32_e32 v71, v64
	v_mov_b32_e32 v72, v64
	v_mov_b32_e32 v73, v64
	v_mov_b32_e32 v74, v64
	v_mov_b32_e32 v75, v64
	v_mov_b32_e32 v76, v64
	v_mov_b32_e32 v77, v64
	v_mov_b32_e32 v78, v64
	v_mov_b32_e32 v79, v64
	v_add_u32_e32 v201, 0xfffe8000, v186
	v_lshlrev_b32_e32 v201, 1, v201
	v_add_u32_e32 v230, 0x10000, v201
	v_add_u32_e32 v231, 0xfffff000, v188
	v_lshlrev_b32_e32 v231, 1, v231
	v_lshlrev_b32_e32 v232, 1, v198
	v_add_u32_e32 v233, 0x440000, v232
	s_mov_b64 s[20:21], s[64:65]
	s_mov_b64 s[22:23], s[60:61]
	s_mov_b64 s[24:25], s[68:69]
.LBB0_1340:
	s_add_u32 s20, s20, 0x20000
	s_addc_u32 s21, s21, 0
	s_add_u32 s22, s22, 0x2000
	s_addc_u32 s23, s23, 0
	s_add_u32 s24, s24, 0x80
	s_addc_u32 s25, s25, 0
	s_add_i32 m0, s52, 0x4000
	s_add_i32 s4, s97, 94
	s_nop 0
	s_nop 0
	s_nop 0
	global_load_lds_dwordx4 v201, s[20:21]
	s_add_i32 m0, s52, 0x6000
	s_nop 0
	global_load_lds_dwordx4 v230, s[20:21]
	s_add_i32 m0, s52, 0xa000
	s_nop 0
	global_load_lds_dwordx4 v231, s[22:23]
	s_add_i32 m0, s52, 0x10000
	s_nop 0
	global_load_lds_dwordx4 v232, s[24:25]
	s_add_i32 m0, s52, 0x12000
	s_nop 0
	global_load_lds_dwordx4 v233, s[24:25]
	s_cmp_gt_i32 s33, s4
	s_cbranch_scc1 .Lat_idle0
	ds_read_b128 v[202:205], v128
	ds_read_b128 v[206:209], v129
	ds_read_b128 v[210:213], v130
	ds_read_b128 v[214:217], v131
	ds_read_b128 v[218:221], v132
	ds_read_b128 v[222:225], v133
	v_fma_f32 v64, v64, s84, -v199
	v_exp_f32_e32 v64, v64
	v_fma_f32 v65, v65, s84, -v199
	v_exp_f32_e32 v65, v65
	v_add_f32_e32 v200, v200, v64
	v_fma_f32 v66, v66, s84, -v199
	v_exp_f32_e32 v66, v66
	v_add_f32_e32 v200, v200, v65
	s_waitcnt lgkmcnt(4)
	v_mfma_f32_32x32x16_bf16 v[80:95], v[202:205], v[96:99], 0
	ds_read_b128 v[202:205], v134
	v_fma_f32 v67, v67, s84, -v199
	v_exp_f32_e32 v67, v67
	v_add_f32_e32 v200, v200, v66
	v_fma_f32 v68, v68, s84, -v199
	v_mfma_f32_32x32x16_bf16 v[80:95], v[206:209], v[100:103], v[80:95]
	ds_read_b128 v[206:209], v135
	v_exp_f32_e32 v68, v68
	v_add_f32_e32 v200, v200, v67
	v_fma_f32 v69, v69, s84, -v199
	v_exp_f32_e32 v69, v69
	s_waitcnt lgkmcnt(4)
	v_mfma_f32_32x32x16_bf16 v[80:95], v[210:213], v[104:107], v[80:95]
	ds_read_b128 v[210:213], v136
	v_add_f32_e32 v200, v200, v68
	v_fma_f32 v70, v70, s84, -v199
	v_exp_f32_e32 v70, v70
	v_add_f32_e32 v200, v200, v69
	v_mfma_f32_32x32x16_bf16 v[80:95], v[214:217], v[108:111], v[80:95]
	ds_read_b128 v[214:217], v137
	v_fma_f32 v71, v71, s84, -v199
	v_exp_f32_e32 v71, v71
	v_add_f32_e32 v200, v200, v70
	v_fma_f32 v72, v72, s84, -v199
	s_waitcnt lgkmcnt(4)
	v_mfma_f32_32x32x16_bf16 v[80:95], v[218:221], v[112:115], v[80:95]
	ds_read_b128 v[218:221], v138
	v_exp_f32_e32 v72, v72
	v_add_f32_e32 v200, v200, v71
	v_fma_f32 v73, v73, s84, -v199
	v_exp_f32_e32 v73, v73
	v_mfma_f32_32x32x16_bf16 v[80:95], v[222:225], v[116:119], v[80:95]
	ds_read_b128 v[222:225], v139
	v_add_f32_e32 v200, v200, v72
	v_fma_f32 v74, v74, s84, -v199
	v_exp_f32_e32 v74, v74
	v_add_f32_e32 v200, v200, v73
	s_waitcnt lgkmcnt(4)
	v_mfma_f32_32x32x16_bf16 v[80:95], v[202:205], v[120:123], v[80:95]
	ds_read_b128 v[164:167], v144 offset:49152
	v_fma_f32 v75, v75, s84, -v199
	v_exp_f32_e32 v75, v75
	v_add_f32_e32 v200, v200, v74
	v_fma_f32 v76, v76, s84, -v199
	v_mfma_f32_32x32x16_bf16 v[80:95], v[206:209], v[124:127], v[80:95]
	ds_read_b128 v[168:171], v144 offset:53248
	v_exp_f32_e32 v76, v76
	v_add_f32_e32 v200, v200, v75
	v_fma_f32 v77, v77, s84, -v199
	v_exp_f32_e32 v77, v77
	s_waitcnt lgkmcnt(4)
	v_mfma_f32_32x32x16_bf16 v[80:95], v[210:213], v[160:163], v[80:95]
	ds_read_b128 v[176:179], v144 offset:57344
	v_add_f32_e32 v200, v200, v76
	v_fma_f32 v78, v78, s84, -v199
	v_exp_f32_e32 v78, v78
	v_add_f32_e32 v200, v200, v77
	v_mfma_f32_32x32x16_bf16 v[80:95], v[214:217], v[152:155], v[80:95]
	ds_read_b128 v[226:229], v144 offset:61440
	v_fma_f32 v79, v79, s84, -v199
	v_exp_f32_e32 v79, v79
	v_add_f32_e32 v200, v200, v78
	v_add_f32_e32 v200, v200, v79
	s_waitcnt lgkmcnt(4)
	v_mfma_f32_32x32x16_bf16 v[80:95], v[218:221], v[156:159], v[80:95]
	v_cvt_pk_bf16_f32 v64, v64, v65
	v_cvt_pk_bf16_f32 v65, v66, v67
	v_cvt_pk_bf16_f32 v66, v68, v69
	v_cvt_pk_bf16_f32 v67, v70, v71
	v_mfma_f32_32x32x16_bf16 v[80:95], v[222:225], v[148:151], v[80:95]
	v_cvt_pk_bf16_f32 v68, v72, v73
	v_cvt_pk_bf16_f32 v69, v74, v75
	v_cvt_pk_bf16_f32 v70, v76, v77
	v_cvt_pk_bf16_f32 v71, v78, v79
	s_waitcnt lgkmcnt(2)
	v_mfma_f32_32x32x16_bf16 v[48:63], v[164:167], v[64:67], v[48:63]
	ds_read_b128 v[164:167], v145 offset:49152
	v_mfma_f32_32x32x16_bf16 v[32:47], v[168:171], v[64:67], v[32:47]
	ds_read_b128 v[168:171], v145 offset:53248
	s_waitcnt lgkmcnt(2)
	v_mfma_f32_32x32x16_bf16 v[16:31], v[176:179], v[64:67], v[16:31]
	ds_read_b128 v[176:179], v145 offset:57344
	v_mfma_f32_32x32x16_bf16 v[0:15], v[226:229], v[64:67], v[0:15]
	ds_read_b128 v[226:229], v145 offset:61440
	ds_read_b128 v[202:205], v128 offset:8192
	ds_read_b128 v[206:209], v129 offset:8192
	ds_read_b128 v[210:213], v130 offset:8192
	ds_read_b128 v[214:217], v131 offset:8192
	ds_read_b128 v[218:221], v132 offset:8192
	ds_read_b128 v[222:225], v133 offset:8192
	s_cmp_gt_i32 s33, s97
	s_cbranch_scc1 .Lat_mask_a0

.Lat_resc_b0_ret:
	s_add_i32 s33, s33, 64
	v_subrev_u32_e32 v197, 64, v197
	s_add_i32 s0, s0, 1
	s_waitcnt vmcnt(0) lgkmcnt(0)
	s_barrier
.Lat_copy1:
	s_add_u32 s20, s20, 0x20000
	s_addc_u32 s21, s21, 0
	s_add_u32 s22, s22, 0x2000
	s_addc_u32 s23, s23, 0
	s_add_u32 s24, s24, 0x80
	s_addc_u32 s25, s25, 0
	s_add_i32 m0, s52, 0x0
	s_add_i32 s4, s97, 94
	s_nop 0
	s_nop 0
	s_nop 0
	global_load_lds_dwordx4 v201, s[20:21]
	s_add_i32 m0, s52, 0x2000
	s_nop 0
	global_load_lds_dwordx4 v230, s[20:21]
	s_add_i32 m0, s52, 0x8000
	s_nop 0
	global_load_lds_dwordx4 v231, s[22:23]
	s_add_i32 m0, s52, 0x14000
	s_nop 0
	global_load_lds_dwordx4 v232, s[24:25]
	s_add_i32 m0, s52, 0x16000
	s_nop 0
	global_load_lds_dwordx4 v233, s[24:25]
	s_cmp_gt_i32 s33, s4
	s_cbranch_scc1 .Lat_idle1
	ds_read_b128 v[202:205], v128 offset:16384
	ds_read_b128 v[206:209], v129 offset:16384
	ds_read_b128 v[210:213], v130 offset:16384
	ds_read_b128 v[214:217], v131 offset:16384
	ds_read_b128 v[218:221], v132 offset:16384
	ds_read_b128 v[222:225], v133 offset:16384
	v_fma_f32 v64, v64, s84, -v199
	v_exp_f32_e32 v64, v64
	v_fma_f32 v65, v65, s84, -v199
	v_exp_f32_e32 v65, v65
	v_add_f32_e32 v200, v200, v64
	v_fma_f32 v66, v66, s84, -v199
	v_exp_f32_e32 v66, v66
	v_add_f32_e32 v200, v200, v65
	s_waitcnt lgkmcnt(4)
	v_mfma_f32_32x32x16_bf16 v[80:95], v[202:205], v[96:99], 0
	ds_read_b128 v[202:205], v134 offset:16384
	v_fma_f32 v67, v67, s84, -v199
	v_exp_f32_e32 v67, v67
	v_add_f32_e32 v200, v200, v66
	v_fma_f32 v68, v68, s84, -v199
	v_mfma_f32_32x32x16_bf16 v[80:95], v[206:209], v[100:103], v[80:95]
	ds_read_b128 v[206:209], v135 offset:16384
	v_exp_f32_e32 v68, v68
	v_add_f32_e32 v200, v200, v67
	v_fma_f32 v69, v69, s84, -v199
	v_exp_f32_e32 v69, v69
	s_waitcnt lgkmcnt(4)
	v_mfma_f32_32x32x16_bf16 v[80:95], v[210:213], v[104:107], v[80:95]
	ds_read_b128 v[210:213], v136 offset:8192
	v_add_f32_e32 v200, v200, v68
	v_fma_f32 v70, v70, s84, -v199
	v_exp_f32_e32 v70, v70
	v_add_f32_e32 v200, v200, v69
	v_mfma_f32_32x32x16_bf16 v[80:95], v[214:217], v[108:111], v[80:95]
	ds_read_b128 v[214:217], v137 offset:8192
	v_fma_f32 v71, v71, s84, -v199
	v_exp_f32_e32 v71, v71
	v_add_f32_e32 v200, v200, v70
	v_fma_f32 v72, v72, s84, -v199
	s_waitcnt lgkmcnt(4)
	v_mfma_f32_32x32x16_bf16 v[80:95], v[218:221], v[112:115], v[80:95]
	ds_read_b128 v[218:221], v138 offset:8192
	v_exp_f32_e32 v72, v72
	v_add_f32_e32 v200, v200, v71
	v_fma_f32 v73, v73, s84, -v199
	v_exp_f32_e32 v73, v73
	v_mfma_f32_32x32x16_bf16 v[80:95], v[222:225], v[116:119], v[80:95]
	ds_read_b128 v[222:225], v139 offset:8192
	v_add_f32_e32 v200, v200, v72
	v_fma_f32 v74, v74, s84, -v199
	v_exp_f32_e32 v74, v74
	v_add_f32_e32 v200, v200, v73
	s_waitcnt lgkmcnt(4)
	v_mfma_f32_32x32x16_bf16 v[80:95], v[202:205], v[120:123], v[80:95]
	ds_read_b128 v[164:167], v144
	v_fma_f32 v75, v75, s84, -v199
	v_exp_f32_e32 v75, v75
	v_add_f32_e32 v200, v200, v74
	v_fma_f32 v76, v76, s84, -v199
	v_mfma_f32_32x32x16_bf16 v[80:95], v[206:209], v[124:127], v[80:95]
	ds_read_b128 v[168:171], v144 offset:4096
	v_exp_f32_e32 v76, v76
	v_add_f32_e32 v200, v200, v75
	v_fma_f32 v77, v77, s84, -v199
	v_exp_f32_e32 v77, v77
	s_waitcnt lgkmcnt(4)
	v_mfma_f32_32x32x16_bf16 v[80:95], v[210:213], v[160:163], v[80:95]
	ds_read_b128 v[176:179], v144 offset:8192
	v_add_f32_e32 v200, v200, v76
	v_fma_f32 v78, v78, s84, -v199
	v_exp_f32_e32 v78, v78
	v_add_f32_e32 v200, v200, v77
	v_mfma_f32_32x32x16_bf16 v[80:95], v[214:217], v[152:155], v[80:95]
	ds_read_b128 v[226:229], v144 offset:12288
	v_fma_f32 v79, v79, s84, -v199
	v_exp_f32_e32 v79, v79
	v_add_f32_e32 v200, v200, v78
	v_add_f32_e32 v200, v200, v79
	s_waitcnt lgkmcnt(4)
	v_mfma_f32_32x32x16_bf16 v[80:95], v[218:221], v[156:159], v[80:95]
	v_cvt_pk_bf16_f32 v64, v64, v65
	v_cvt_pk_bf16_f32 v65, v66, v67
	v_cvt_pk_bf16_f32 v66, v68, v69
	v_cvt_pk_bf16_f32 v67, v70, v71
	v_mfma_f32_32x32x16_bf16 v[80:95], v[222:225], v[148:151], v[80:95]
	v_cvt_pk_bf16_f32 v68, v72, v73
	v_cvt_pk_bf16_f32 v69, v74, v75
	v_cvt_pk_bf16_f32 v70, v76, v77
	v_cvt_pk_bf16_f32 v71, v78, v79
	s_waitcnt lgkmcnt(2)
	v_mfma_f32_32x32x16_bf16 v[48:63], v[164:167], v[64:67], v[48:63]
	ds_read_b128 v[164:167], v145
	v_mfma_f32_32x32x16_bf16 v[32:47], v[168:171], v[64:67], v[32:47]
	ds_read_b128 v[168:171], v145 offset:4096
	s_waitcnt lgkmcnt(2)
	v_mfma_f32_32x32x16_bf16 v[16:31], v[176:179], v[64:67], v[16:31]
	ds_read_b128 v[176:179], v145 offset:8192
	v_mfma_f32_32x32x16_bf16 v[0:15], v[226:229], v[64:67], v[0:15]
	ds_read_b128 v[226:229], v145 offset:12288
	ds_read_b128 v[202:205], v128 offset:24576
	ds_read_b128 v[206:209], v129 offset:24576
	ds_read_b128 v[210:213], v130 offset:24576
	ds_read_b128 v[214:217], v131 offset:24576
	ds_read_b128 v[218:221], v132 offset:24576
	ds_read_b128 v[222:225], v133 offset:24576
	s_cmp_gt_i32 s33, s97
	s_cbranch_scc1 .Lat_mask_a1

.Lat_resc_a1_ret:
	v_fma_f32 v80, v80, s84, -v199
	v_exp_f32_e32 v80, v80
	v_fma_f32 v81, v81, s84, -v199
	v_exp_f32_e32 v81, v81
	v_add_f32_e32 v200, v200, v80
	v_fma_f32 v82, v82, s84, -v199
	v_exp_f32_e32 v82, v82
	v_add_f32_e32 v200, v200, v81
	s_waitcnt lgkmcnt(4)
	v_mfma_f32_32x32x16_bf16 v[64:79], v[202:205], v[96:99], 0
	ds_read_b128 v[202:205], v134 offset:24576
	v_fma_f32 v83, v83, s84, -v199
	v_exp_f32_e32 v83, v83
	v_add_f32_e32 v200, v200, v82
	v_fma_f32 v84, v84, s84, -v199
	v_mfma_f32_32x32x16_bf16 v[64:79], v[206:209], v[100:103], v[64:79]
	ds_read_b128 v[206:209], v135 offset:24576
	v_exp_f32_e32 v84, v84
	v_add_f32_e32 v200, v200, v83
	v_fma_f32 v85, v85, s84, -v199
	v_exp_f32_e32 v85, v85
	s_waitcnt lgkmcnt(4)
	v_mfma_f32_32x32x16_bf16 v[64:79], v[210:213], v[104:107], v[64:79]
	ds_read_b128 v[210:213], v136 offset:12288
	v_add_f32_e32 v200, v200, v84
	v_fma_f32 v86, v86, s84, -v199
	v_exp_f32_e32 v86, v86
	v_add_f32_e32 v200, v200, v85
	v_mfma_f32_32x32x16_bf16 v[64:79], v[214:217], v[108:111], v[64:79]
	ds_read_b128 v[214:217], v137 offset:12288
	v_fma_f32 v87, v87, s84, -v199
	v_exp_f32_e32 v87, v87
	v_add_f32_e32 v200, v200, v86
	v_fma_f32 v88, v88, s84, -v199
	s_waitcnt lgkmcnt(4)
	v_mfma_f32_32x32x16_bf16 v[64:79], v[218:221], v[112:115], v[64:79]
	ds_read_b128 v[218:221], v138 offset:12288
	v_exp_f32_e32 v88, v88
	v_add_f32_e32 v200, v200, v87
	v_fma_f32 v89, v89, s84, -v199
	v_exp_f32_e32 v89, v89
	v_mfma_f32_32x32x16_bf16 v[64:79], v[222:225], v[116:119], v[64:79]
	ds_read_b128 v[222:225], v139 offset:12288
	v_add_f32_e32 v200, v200, v88
	v_fma_f32 v90, v90, s84, -v199
	v_exp_f32_e32 v90, v90
	v_add_f32_e32 v200, v200, v89
	s_waitcnt lgkmcnt(4)
	v_mfma_f32_32x32x16_bf16 v[64:79], v[202:205], v[120:123], v[64:79]
	ds_read_b128 v[164:167], v140 offset:16384
	v_fma_f32 v91, v91, s84, -v199
	v_exp_f32_e32 v91, v91
	v_add_f32_e32 v200, v200, v90
	v_fma_f32 v92, v92, s84, -v199
	v_mfma_f32_32x32x16_bf16 v[64:79], v[206:209], v[124:127], v[64:79]
	ds_read_b128 v[168:171], v140 offset:20480
	v_exp_f32_e32 v92, v92
	v_add_f32_e32 v200, v200, v91
	v_fma_f32 v93, v93, s84, -v199
	v_exp_f32_e32 v93, v93
	s_waitcnt lgkmcnt(4)
	v_mfma_f32_32x32x16_bf16 v[64:79], v[210:213], v[160:163], v[64:79]
	ds_read_b128 v[176:179], v140 offset:24576
	v_add_f32_e32 v200, v200, v92
	v_fma_f32 v94, v94, s84, -v199
	v_exp_f32_e32 v94, v94
	v_add_f32_e32 v200, v200, v93
	v_mfma_f32_32x32x16_bf16 v[64:79], v[214:217], v[152:155], v[64:79]
	ds_read_b128 v[226:229], v140 offset:28672
	v_fma_f32 v95, v95, s84, -v199
	v_exp_f32_e32 v95, v95
	v_add_f32_e32 v200, v200, v94
	v_add_f32_e32 v200, v200, v95
	s_waitcnt lgkmcnt(4)
	v_mfma_f32_32x32x16_bf16 v[64:79], v[218:221], v[156:159], v[64:79]
	v_cvt_pk_bf16_f32 v80, v80, v81
	v_cvt_pk_bf16_f32 v81, v82, v83
	v_cvt_pk_bf16_f32 v82, v84, v85
	v_cvt_pk_bf16_f32 v83, v86, v87
	v_mfma_f32_32x32x16_bf16 v[64:79], v[222:225], v[148:151], v[64:79]
	v_cvt_pk_bf16_f32 v84, v88, v89
	v_cvt_pk_bf16_f32 v85, v90, v91
	v_cvt_pk_bf16_f32 v86, v92, v93
	v_cvt_pk_bf16_f32 v87, v94, v95
	s_waitcnt lgkmcnt(2)
	v_mfma_f32_32x32x16_bf16 v[48:63], v[164:167], v[80:83], v[48:63]
	ds_read_b128 v[164:167], v141 offset:16384
	v_mfma_f32_32x32x16_bf16 v[32:47], v[168:171], v[80:83], v[32:47]
	ds_read_b128 v[168:171], v141 offset:20480
	s_waitcnt lgkmcnt(2)
	v_mfma_f32_32x32x16_bf16 v[16:31], v[176:179], v[80:83], v[16:31]
	ds_read_b128 v[176:179], v141 offset:24576
	v_mfma_f32_32x32x16_bf16 v[0:15], v[226:229], v[80:83], v[0:15]
	ds_read_b128 v[226:229], v141 offset:28672
	s_cmp_gt_i32 s33, s97
	s_cbranch_scc1 .Lat_mask_b1

.Lat_copy2:
	s_add_u32 s20, s20, 0x20000
	s_addc_u32 s21, s21, 0
	s_add_u32 s22, s22, 0x2000
	s_addc_u32 s23, s23, 0
	s_add_u32 s24, s24, 0x80
	s_addc_u32 s25, s25, 0
	s_add_i32 m0, s52, 0x4000
	s_add_i32 s4, s97, 94
	s_nop 0
	s_nop 0
	s_nop 0
	global_load_lds_dwordx4 v201, s[20:21]
	s_add_i32 m0, s52, 0x6000
	s_nop 0
	global_load_lds_dwordx4 v230, s[20:21]
	s_add_i32 m0, s52, 0xa000
	s_nop 0
	global_load_lds_dwordx4 v231, s[22:23]
	s_add_i32 m0, s52, 0x18000
	s_nop 0
	global_load_lds_dwordx4 v232, s[24:25]
	s_add_i32 m0, s52, 0x1a000
	s_nop 0
	global_load_lds_dwordx4 v233, s[24:25]
	s_cmp_gt_i32 s33, s4
	s_cbranch_scc1 .Lat_idle2
	ds_read_b128 v[202:205], v128
	ds_read_b128 v[206:209], v129
	ds_read_b128 v[210:213], v130
	ds_read_b128 v[214:217], v131
	ds_read_b128 v[218:221], v132
	ds_read_b128 v[222:225], v133
	v_fma_f32 v64, v64, s84, -v199
	v_exp_f32_e32 v64, v64
	v_fma_f32 v65, v65, s84, -v199
	v_exp_f32_e32 v65, v65
	v_add_f32_e32 v200, v200, v64
	v_fma_f32 v66, v66, s84, -v199
	v_exp_f32_e32 v66, v66
	v_add_f32_e32 v200, v200, v65
	s_waitcnt lgkmcnt(4)
	v_mfma_f32_32x32x16_bf16 v[80:95], v[202:205], v[96:99], 0
	ds_read_b128 v[202:205], v134
	v_fma_f32 v67, v67, s84, -v199
	v_exp_f32_e32 v67, v67
	v_add_f32_e32 v200, v200, v66
	v_fma_f32 v68, v68, s84, -v199
	v_mfma_f32_32x32x16_bf16 v[80:95], v[206:209], v[100:103], v[80:95]
	ds_read_b128 v[206:209], v135
	v_exp_f32_e32 v68, v68
	v_add_f32_e32 v200, v200, v67
	v_fma_f32 v69, v69, s84, -v199
	v_exp_f32_e32 v69, v69
	s_waitcnt lgkmcnt(4)
	v_mfma_f32_32x32x16_bf16 v[80:95], v[210:213], v[104:107], v[80:95]
	ds_read_b128 v[210:213], v136
	v_add_f32_e32 v200, v200, v68
	v_fma_f32 v70, v70, s84, -v199
	v_exp_f32_e32 v70, v70
	v_add_f32_e32 v200, v200, v69
	v_mfma_f32_32x32x16_bf16 v[80:95], v[214:217], v[108:111], v[80:95]
	ds_read_b128 v[214:217], v137
	v_fma_f32 v71, v71, s84, -v199
	v_exp_f32_e32 v71, v71
	v_add_f32_e32 v200, v200, v70
	v_fma_f32 v72, v72, s84, -v199
	s_waitcnt lgkmcnt(4)
	v_mfma_f32_32x32x16_bf16 v[80:95], v[218:221], v[112:115], v[80:95]
	ds_read_b128 v[218:221], v138
	v_exp_f32_e32 v72, v72
	v_add_f32_e32 v200, v200, v71
	v_fma_f32 v73, v73, s84, -v199
	v_exp_f32_e32 v73, v73
	v_mfma_f32_32x32x16_bf16 v[80:95], v[222:225], v[116:119], v[80:95]
	ds_read_b128 v[222:225], v139
	v_add_f32_e32 v200, v200, v72
	v_fma_f32 v74, v74, s84, -v199
	v_exp_f32_e32 v74, v74
	v_add_f32_e32 v200, v200, v73
	s_waitcnt lgkmcnt(4)
	v_mfma_f32_32x32x16_bf16 v[80:95], v[202:205], v[120:123], v[80:95]
	ds_read_b128 v[164:167], v144 offset:16384
	v_fma_f32 v75, v75, s84, -v199
	v_exp_f32_e32 v75, v75
	v_add_f32_e32 v200, v200, v74
	v_fma_f32 v76, v76, s84, -v199
	v_mfma_f32_32x32x16_bf16 v[80:95], v[206:209], v[124:127], v[80:95]
	ds_read_b128 v[168:171], v144 offset:20480
	v_exp_f32_e32 v76, v76
	v_add_f32_e32 v200, v200, v75
	v_fma_f32 v77, v77, s84, -v199
	v_exp_f32_e32 v77, v77
	s_waitcnt lgkmcnt(4)
	v_mfma_f32_32x32x16_bf16 v[80:95], v[210:213], v[160:163], v[80:95]
	ds_read_b128 v[176:179], v144 offset:24576
	v_add_f32_e32 v200, v200, v76
	v_fma_f32 v78, v78, s84, -v199
	v_exp_f32_e32 v78, v78
	v_add_f32_e32 v200, v200, v77
	v_mfma_f32_32x32x16_bf16 v[80:95], v[214:217], v[152:155], v[80:95]
	ds_read_b128 v[226:229], v144 offset:28672
	v_fma_f32 v79, v79, s84, -v199
	v_exp_f32_e32 v79, v79
	v_add_f32_e32 v200, v200, v78
	v_add_f32_e32 v200, v200, v79
	s_waitcnt lgkmcnt(4)
	v_mfma_f32_32x32x16_bf16 v[80:95], v[218:221], v[156:159], v[80:95]
	v_cvt_pk_bf16_f32 v64, v64, v65
	v_cvt_pk_bf16_f32 v65, v66, v67
	v_cvt_pk_bf16_f32 v66, v68, v69
	v_cvt_pk_bf16_f32 v67, v70, v71
	v_mfma_f32_32x32x16_bf16 v[80:95], v[222:225], v[148:151], v[80:95]
	v_cvt_pk_bf16_f32 v68, v72, v73
	v_cvt_pk_bf16_f32 v69, v74, v75
	v_cvt_pk_bf16_f32 v70, v76, v77
	v_cvt_pk_bf16_f32 v71, v78, v79
	s_waitcnt lgkmcnt(2)
	v_mfma_f32_32x32x16_bf16 v[48:63], v[164:167], v[64:67], v[48:63]
	ds_read_b128 v[164:167], v145 offset:16384
	v_mfma_f32_32x32x16_bf16 v[32:47], v[168:171], v[64:67], v[32:47]
	ds_read_b128 v[168:171], v145 offset:20480
	s_waitcnt lgkmcnt(2)
	v_mfma_f32_32x32x16_bf16 v[16:31], v[176:179], v[64:67], v[16:31]
	ds_read_b128 v[176:179], v145 offset:24576
	v_mfma_f32_32x32x16_bf16 v[0:15], v[226:229], v[64:67], v[0:15]
	ds_read_b128 v[226:229], v145 offset:28672
	ds_read_b128 v[202:205], v128 offset:8192
	ds_read_b128 v[206:209], v129 offset:8192
	ds_read_b128 v[210:213], v130 offset:8192
	ds_read_b128 v[214:217], v131 offset:8192
	ds_read_b128 v[218:221], v132 offset:8192
	ds_read_b128 v[222:225], v133 offset:8192
	s_cmp_gt_i32 s33, s97
	s_cbranch_scc1 .Lat_mask_a2

.Lat_resc_a2_ret:
	v_fma_f32 v80, v80, s84, -v199
	v_exp_f32_e32 v80, v80
	v_fma_f32 v81, v81, s84, -v199
	v_exp_f32_e32 v81, v81
	v_add_f32_e32 v200, v200, v80
	v_fma_f32 v82, v82, s84, -v199
	v_exp_f32_e32 v82, v82
	v_add_f32_e32 v200, v200, v81
	s_waitcnt lgkmcnt(4)
	v_mfma_f32_32x32x16_bf16 v[64:79], v[202:205], v[96:99], 0
	ds_read_b128 v[202:205], v134 offset:8192
	v_fma_f32 v83, v83, s84, -v199
	v_exp_f32_e32 v83, v83
	v_add_f32_e32 v200, v200, v82
	v_fma_f32 v84, v84, s84, -v199
	v_mfma_f32_32x32x16_bf16 v[64:79], v[206:209], v[100:103], v[64:79]
	ds_read_b128 v[206:209], v135 offset:8192
	v_exp_f32_e32 v84, v84
	v_add_f32_e32 v200, v200, v83
	v_fma_f32 v85, v85, s84, -v199
	v_exp_f32_e32 v85, v85
	s_waitcnt lgkmcnt(4)
	v_mfma_f32_32x32x16_bf16 v[64:79], v[210:213], v[104:107], v[64:79]
	ds_read_b128 v[210:213], v136 offset:4096
	v_add_f32_e32 v200, v200, v84
	v_fma_f32 v86, v86, s84, -v199
	v_exp_f32_e32 v86, v86
	v_add_f32_e32 v200, v200, v85
	v_mfma_f32_32x32x16_bf16 v[64:79], v[214:217], v[108:111], v[64:79]
	ds_read_b128 v[214:217], v137 offset:4096
	v_fma_f32 v87, v87, s84, -v199
	v_exp_f32_e32 v87, v87
	v_add_f32_e32 v200, v200, v86
	v_fma_f32 v88, v88, s84, -v199
	s_waitcnt lgkmcnt(4)
	v_mfma_f32_32x32x16_bf16 v[64:79], v[218:221], v[112:115], v[64:79]
	ds_read_b128 v[218:221], v138 offset:4096
	v_exp_f32_e32 v88, v88
	v_add_f32_e32 v200, v200, v87
	v_fma_f32 v89, v89, s84, -v199
	v_exp_f32_e32 v89, v89
	v_mfma_f32_32x32x16_bf16 v[64:79], v[222:225], v[116:119], v[64:79]
	ds_read_b128 v[222:225], v139 offset:4096
	v_add_f32_e32 v200, v200, v88
	v_fma_f32 v90, v90, s84, -v199
	v_exp_f32_e32 v90, v90
	v_add_f32_e32 v200, v200, v89
	s_waitcnt lgkmcnt(4)
	v_mfma_f32_32x32x16_bf16 v[64:79], v[202:205], v[120:123], v[64:79]
	ds_read_b128 v[164:167], v140 offset:32768
	v_fma_f32 v91, v91, s84, -v199
	v_exp_f32_e32 v91, v91
	v_add_f32_e32 v200, v200, v90
	v_fma_f32 v92, v92, s84, -v199
	v_mfma_f32_32x32x16_bf16 v[64:79], v[206:209], v[124:127], v[64:79]
	ds_read_b128 v[168:171], v140 offset:36864
	v_exp_f32_e32 v92, v92
	v_add_f32_e32 v200, v200, v91
	v_fma_f32 v93, v93, s84, -v199
	v_exp_f32_e32 v93, v93
	s_waitcnt lgkmcnt(4)
	v_mfma_f32_32x32x16_bf16 v[64:79], v[210:213], v[160:163], v[64:79]
	ds_read_b128 v[176:179], v140 offset:40960
	v_add_f32_e32 v200, v200, v92
	v_fma_f32 v94, v94, s84, -v199
	v_exp_f32_e32 v94, v94
	v_add_f32_e32 v200, v200, v93
	v_mfma_f32_32x32x16_bf16 v[64:79], v[214:217], v[152:155], v[64:79]
	ds_read_b128 v[226:229], v140 offset:45056
	v_fma_f32 v95, v95, s84, -v199
	v_exp_f32_e32 v95, v95
	v_add_f32_e32 v200, v200, v94
	v_add_f32_e32 v200, v200, v95
	s_waitcnt lgkmcnt(4)
	v_mfma_f32_32x32x16_bf16 v[64:79], v[218:221], v[156:159], v[64:79]
	v_cvt_pk_bf16_f32 v80, v80, v81
	v_cvt_pk_bf16_f32 v81, v82, v83
	v_cvt_pk_bf16_f32 v82, v84, v85
	v_cvt_pk_bf16_f32 v83, v86, v87
	v_mfma_f32_32x32x16_bf16 v[64:79], v[222:225], v[148:151], v[64:79]
	v_cvt_pk_bf16_f32 v84, v88, v89
	v_cvt_pk_bf16_f32 v85, v90, v91
	v_cvt_pk_bf16_f32 v86, v92, v93
	v_cvt_pk_bf16_f32 v87, v94, v95
	s_waitcnt lgkmcnt(2)
	v_mfma_f32_32x32x16_bf16 v[48:63], v[164:167], v[80:83], v[48:63]
	ds_read_b128 v[164:167], v141 offset:32768
	v_mfma_f32_32x32x16_bf16 v[32:47], v[168:171], v[80:83], v[32:47]
	ds_read_b128 v[168:171], v141 offset:36864
	s_waitcnt lgkmcnt(2)
	v_mfma_f32_32x32x16_bf16 v[16:31], v[176:179], v[80:83], v[16:31]
	ds_read_b128 v[176:179], v141 offset:40960
	v_mfma_f32_32x32x16_bf16 v[0:15], v[226:229], v[80:83], v[0:15]
	ds_read_b128 v[226:229], v141 offset:45056
	s_cmp_gt_i32 s33, s97
	s_cbranch_scc1 .Lat_mask_b2

.Lat_copy3:
	s_add_i32 s4, s0, 1
	s_cmp_lt_i32 s4, s53
	s_cbranch_scc0 .Lat_skip_ld
	s_add_u32 s20, s20, 0x20000
	s_addc_u32 s21, s21, 0
	s_add_u32 s22, s22, 0x2000
	s_addc_u32 s23, s23, 0
	s_add_u32 s24, s24, 0x80
	s_addc_u32 s25, s25, 0
	s_add_i32 m0, s52, 0x0
	s_add_i32 s4, s97, 94
	s_nop 0
	s_nop 0
	s_nop 0
	global_load_lds_dwordx4 v201, s[20:21]
	s_add_i32 m0, s52, 0x2000
	s_nop 0
	global_load_lds_dwordx4 v230, s[20:21]
	s_add_i32 m0, s52, 0x8000
	s_nop 0
	global_load_lds_dwordx4 v231, s[22:23]
	s_add_i32 m0, s52, 0xc000
	s_nop 0
	global_load_lds_dwordx4 v232, s[24:25]
	s_add_i32 m0, s52, 0xe000
	s_nop 0
	global_load_lds_dwordx4 v233, s[24:25]
.Lat_skip_ld:
	s_add_i32 s4, s97, 94
	s_cmp_gt_i32 s33, s4
	s_cbranch_scc1 .Lat_idle3
	ds_read_b128 v[202:205], v128 offset:16384
	ds_read_b128 v[206:209], v129 offset:16384
	ds_read_b128 v[210:213], v130 offset:16384
	ds_read_b128 v[214:217], v131 offset:16384
	ds_read_b128 v[218:221], v132 offset:16384
	ds_read_b128 v[222:225], v133 offset:16384
	v_fma_f32 v64, v64, s84, -v199
	v_exp_f32_e32 v64, v64
	v_fma_f32 v65, v65, s84, -v199
	v_exp_f32_e32 v65, v65
	v_add_f32_e32 v200, v200, v64
	v_fma_f32 v66, v66, s84, -v199
	v_exp_f32_e32 v66, v66
	v_add_f32_e32 v200, v200, v65
	s_waitcnt lgkmcnt(4)
	v_mfma_f32_32x32x16_bf16 v[80:95], v[202:205], v[96:99], 0
	ds_read_b128 v[202:205], v134 offset:16384
	v_fma_f32 v67, v67, s84, -v199
	v_exp_f32_e32 v67, v67
	v_add_f32_e32 v200, v200, v66
	v_fma_f32 v68, v68, s84, -v199
	v_mfma_f32_32x32x16_bf16 v[80:95], v[206:209], v[100:103], v[80:95]
	ds_read_b128 v[206:209], v135 offset:16384
	v_exp_f32_e32 v68, v68
	v_add_f32_e32 v200, v200, v67
	v_fma_f32 v69, v69, s84, -v199
	v_exp_f32_e32 v69, v69
	s_waitcnt lgkmcnt(4)
	v_mfma_f32_32x32x16_bf16 v[80:95], v[210:213], v[104:107], v[80:95]
	ds_read_b128 v[210:213], v136 offset:8192
	v_add_f32_e32 v200, v200, v68
	v_fma_f32 v70, v70, s84, -v199
	v_exp_f32_e32 v70, v70
	v_add_f32_e32 v200, v200, v69
	v_mfma_f32_32x32x16_bf16 v[80:95], v[214:217], v[108:111], v[80:95]
	ds_read_b128 v[214:217], v137 offset:8192
	v_fma_f32 v71, v71, s84, -v199
	v_exp_f32_e32 v71, v71
	v_add_f32_e32 v200, v200, v70
	v_fma_f32 v72, v72, s84, -v199
	s_waitcnt lgkmcnt(4)
	v_mfma_f32_32x32x16_bf16 v[80:95], v[218:221], v[112:115], v[80:95]
	ds_read_b128 v[218:221], v138 offset:8192
	v_exp_f32_e32 v72, v72
	v_add_f32_e32 v200, v200, v71
	v_fma_f32 v73, v73, s84, -v199
	v_exp_f32_e32 v73, v73
	v_mfma_f32_32x32x16_bf16 v[80:95], v[222:225], v[116:119], v[80:95]
	ds_read_b128 v[222:225], v139 offset:8192
	v_add_f32_e32 v200, v200, v72
	v_fma_f32 v74, v74, s84, -v199
	v_exp_f32_e32 v74, v74
	v_add_f32_e32 v200, v200, v73
	s_waitcnt lgkmcnt(4)
	v_mfma_f32_32x32x16_bf16 v[80:95], v[202:205], v[120:123], v[80:95]
	ds_read_b128 v[164:167], v144 offset:32768
	v_fma_f32 v75, v75, s84, -v199
	v_exp_f32_e32 v75, v75
	v_add_f32_e32 v200, v200, v74
	v_fma_f32 v76, v76, s84, -v199
	v_mfma_f32_32x32x16_bf16 v[80:95], v[206:209], v[124:127], v[80:95]
	ds_read_b128 v[168:171], v144 offset:36864
	v_exp_f32_e32 v76, v76
	v_add_f32_e32 v200, v200, v75
	v_fma_f32 v77, v77, s84, -v199
	v_exp_f32_e32 v77, v77
	s_waitcnt lgkmcnt(4)
	v_mfma_f32_32x32x16_bf16 v[80:95], v[210:213], v[160:163], v[80:95]
	ds_read_b128 v[176:179], v144 offset:40960
	v_add_f32_e32 v200, v200, v76
	v_fma_f32 v78, v78, s84, -v199
	v_exp_f32_e32 v78, v78
	v_add_f32_e32 v200, v200, v77
	v_mfma_f32_32x32x16_bf16 v[80:95], v[214:217], v[152:155], v[80:95]
	ds_read_b128 v[226:229], v144 offset:45056
	v_fma_f32 v79, v79, s84, -v199
	v_exp_f32_e32 v79, v79
	v_add_f32_e32 v200, v200, v78
	v_add_f32_e32 v200, v200, v79
	s_waitcnt lgkmcnt(4)
	v_mfma_f32_32x32x16_bf16 v[80:95], v[218:221], v[156:159], v[80:95]
	v_cvt_pk_bf16_f32 v64, v64, v65
	v_cvt_pk_bf16_f32 v65, v66, v67
	v_cvt_pk_bf16_f32 v66, v68, v69
	v_cvt_pk_bf16_f32 v67, v70, v71
	v_mfma_f32_32x32x16_bf16 v[80:95], v[222:225], v[148:151], v[80:95]
	v_cvt_pk_bf16_f32 v68, v72, v73
	v_cvt_pk_bf16_f32 v69, v74, v75
	v_cvt_pk_bf16_f32 v70, v76, v77
	v_cvt_pk_bf16_f32 v71, v78, v79
	s_waitcnt lgkmcnt(2)
	v_mfma_f32_32x32x16_bf16 v[48:63], v[164:167], v[64:67], v[48:63]
	ds_read_b128 v[164:167], v145 offset:32768
	v_mfma_f32_32x32x16_bf16 v[32:47], v[168:171], v[64:67], v[32:47]
	ds_read_b128 v[168:171], v145 offset:36864
	s_waitcnt lgkmcnt(2)
	v_mfma_f32_32x32x16_bf16 v[16:31], v[176:179], v[64:67], v[16:31]
	ds_read_b128 v[176:179], v145 offset:40960
	v_mfma_f32_32x32x16_bf16 v[0:15], v[226:229], v[64:67], v[0:15]
	ds_read_b128 v[226:229], v145 offset:45056
	ds_read_b128 v[202:205], v128 offset:24576
	ds_read_b128 v[206:209], v129 offset:24576
	ds_read_b128 v[210:213], v130 offset:24576
	ds_read_b128 v[214:217], v131 offset:24576
	ds_read_b128 v[218:221], v132 offset:24576
	ds_read_b128 v[222:225], v133 offset:24576
	s_cmp_gt_i32 s33, s97
	s_cbranch_scc1 .Lat_mask_a3

.Lat_resc_a3_ret:
	v_fma_f32 v80, v80, s84, -v199
	v_exp_f32_e32 v80, v80
	v_fma_f32 v81, v81, s84, -v199
	v_exp_f32_e32 v81, v81
	v_add_f32_e32 v200, v200, v80
	v_fma_f32 v82, v82, s84, -v199
	v_exp_f32_e32 v82, v82
	v_add_f32_e32 v200, v200, v81
	s_waitcnt lgkmcnt(4)
	v_mfma_f32_32x32x16_bf16 v[64:79], v[202:205], v[96:99], 0
	ds_read_b128 v[202:205], v134 offset:24576
	v_fma_f32 v83, v83, s84, -v199
	v_exp_f32_e32 v83, v83
	v_add_f32_e32 v200, v200, v82
	v_fma_f32 v84, v84, s84, -v199
	v_mfma_f32_32x32x16_bf16 v[64:79], v[206:209], v[100:103], v[64:79]
	ds_read_b128 v[206:209], v135 offset:24576
	v_exp_f32_e32 v84, v84
	v_add_f32_e32 v200, v200, v83
	v_fma_f32 v85, v85, s84, -v199
	v_exp_f32_e32 v85, v85
	s_waitcnt lgkmcnt(4)
	v_mfma_f32_32x32x16_bf16 v[64:79], v[210:213], v[104:107], v[64:79]
	ds_read_b128 v[210:213], v136 offset:12288
	v_add_f32_e32 v200, v200, v84
	v_fma_f32 v86, v86, s84, -v199
	v_exp_f32_e32 v86, v86
	v_add_f32_e32 v200, v200, v85
	v_mfma_f32_32x32x16_bf16 v[64:79], v[214:217], v[108:111], v[64:79]
	ds_read_b128 v[214:217], v137 offset:12288
	v_fma_f32 v87, v87, s84, -v199
	v_exp_f32_e32 v87, v87
	v_add_f32_e32 v200, v200, v86
	v_fma_f32 v88, v88, s84, -v199
	s_waitcnt lgkmcnt(4)
	v_mfma_f32_32x32x16_bf16 v[64:79], v[218:221], v[112:115], v[64:79]
	ds_read_b128 v[218:221], v138 offset:12288
	v_exp_f32_e32 v88, v88
	v_add_f32_e32 v200, v200, v87
	v_fma_f32 v89, v89, s84, -v199
	v_exp_f32_e32 v89, v89
	v_mfma_f32_32x32x16_bf16 v[64:79], v[222:225], v[116:119], v[64:79]
	ds_read_b128 v[222:225], v139 offset:12288
	v_add_f32_e32 v200, v200, v88
	v_fma_f32 v90, v90, s84, -v199
	v_exp_f32_e32 v90, v90
	v_add_f32_e32 v200, v200, v89
	s_waitcnt lgkmcnt(4)
	v_mfma_f32_32x32x16_bf16 v[64:79], v[202:205], v[120:123], v[64:79]
	ds_read_b128 v[164:167], v140 offset:49152
	v_fma_f32 v91, v91, s84, -v199
	v_exp_f32_e32 v91, v91
	v_add_f32_e32 v200, v200, v90
	v_fma_f32 v92, v92, s84, -v199
	v_mfma_f32_32x32x16_bf16 v[64:79], v[206:209], v[124:127], v[64:79]
	ds_read_b128 v[168:171], v140 offset:53248
	v_exp_f32_e32 v92, v92
	v_add_f32_e32 v200, v200, v91
	v_fma_f32 v93, v93, s84, -v199
	v_exp_f32_e32 v93, v93
	s_waitcnt lgkmcnt(4)
	v_mfma_f32_32x32x16_bf16 v[64:79], v[210:213], v[160:163], v[64:79]
	ds_read_b128 v[176:179], v140 offset:57344
	v_add_f32_e32 v200, v200, v92
	v_fma_f32 v94, v94, s84, -v199
	v_exp_f32_e32 v94, v94
	v_add_f32_e32 v200, v200, v93
	v_mfma_f32_32x32x16_bf16 v[64:79], v[214:217], v[152:155], v[64:79]
	ds_read_b128 v[226:229], v140 offset:61440
	v_fma_f32 v95, v95, s84, -v199
	v_exp_f32_e32 v95, v95
	v_add_f32_e32 v200, v200, v94
	v_add_f32_e32 v200, v200, v95
	s_waitcnt lgkmcnt(4)
	v_mfma_f32_32x32x16_bf16 v[64:79], v[218:221], v[156:159], v[64:79]
	v_cvt_pk_bf16_f32 v80, v80, v81
	v_cvt_pk_bf16_f32 v81, v82, v83
	v_cvt_pk_bf16_f32 v82, v84, v85
	v_cvt_pk_bf16_f32 v83, v86, v87
	v_mfma_f32_32x32x16_bf16 v[64:79], v[222:225], v[148:151], v[64:79]
	v_cvt_pk_bf16_f32 v84, v88, v89
	v_cvt_pk_bf16_f32 v85, v90, v91
	v_cvt_pk_bf16_f32 v86, v92, v93
	v_cvt_pk_bf16_f32 v87, v94, v95
	s_waitcnt lgkmcnt(2)
	v_mfma_f32_32x32x16_bf16 v[48:63], v[164:167], v[80:83], v[48:63]
	ds_read_b128 v[164:167], v141 offset:49152
	v_mfma_f32_32x32x16_bf16 v[32:47], v[168:171], v[80:83], v[32:47]
	ds_read_b128 v[168:171], v141 offset:53248
	s_waitcnt lgkmcnt(2)
	v_mfma_f32_32x32x16_bf16 v[16:31], v[176:179], v[80:83], v[16:31]
	ds_read_b128 v[176:179], v141 offset:57344
	v_mfma_f32_32x32x16_bf16 v[0:15], v[226:229], v[80:83], v[0:15]
	ds_read_b128 v[226:229], v141 offset:61440
	s_cmp_gt_i32 s33, s97
	s_cbranch_scc1 .Lat_mask_b3

.Lat_resc_b3_ret:
	s_add_i32 s33, s33, 64
	v_subrev_u32_e32 v197, 64, v197
	s_add_i32 s0, s0, 1
	s_cmp_eq_u32 s53, s0
	s_waitcnt vmcnt(0) lgkmcnt(0)
	s_barrier
	s_cbranch_scc0 .LBB0_1340
	v_fma_f32 v64, v64, s84, -v199
	v_exp_f32_e32 v64, v64
	v_fma_f32 v65, v65, s84, -v199
	v_exp_f32_e32 v65, v65
	v_add_f32_e32 v200, v200, v64
	v_fma_f32 v66, v66, s84, -v199
	v_exp_f32_e32 v66, v66
	v_add_f32_e32 v200, v200, v65
	v_fma_f32 v67, v67, s84, -v199
	v_exp_f32_e32 v67, v67
	v_add_f32_e32 v200, v200, v66
	v_fma_f32 v68, v68, s84, -v199
	v_exp_f32_e32 v68, v68
	v_add_f32_e32 v200, v200, v67
	v_fma_f32 v69, v69, s84, -v199
	v_exp_f32_e32 v69, v69
	v_add_f32_e32 v200, v200, v68
	v_fma_f32 v70, v70, s84, -v199
	v_exp_f32_e32 v70, v70
	v_add_f32_e32 v200, v200, v69
	v_fma_f32 v71, v71, s84, -v199
	v_exp_f32_e32 v71, v71
	v_add_f32_e32 v200, v200, v70
	v_fma_f32 v72, v72, s84, -v199
	v_exp_f32_e32 v72, v72
	v_add_f32_e32 v200, v200, v71
	v_fma_f32 v73, v73, s84, -v199
	v_exp_f32_e32 v73, v73
	v_add_f32_e32 v200, v200, v72
	v_fma_f32 v74, v74, s84, -v199
	v_exp_f32_e32 v74, v74
	v_add_f32_e32 v200, v200, v73
	v_fma_f32 v75, v75, s84, -v199
	v_exp_f32_e32 v75, v75
	v_add_f32_e32 v200, v200, v74
	v_fma_f32 v76, v76, s84, -v199
	v_exp_f32_e32 v76, v76
	v_add_f32_e32 v200, v200, v75
	v_fma_f32 v77, v77, s84, -v199
	v_exp_f32_e32 v77, v77
	v_add_f32_e32 v200, v200, v76
	v_fma_f32 v78, v78, s84, -v199
	v_exp_f32_e32 v78, v78
	v_add_f32_e32 v200, v200, v77
	v_fma_f32 v79, v79, s84, -v199
	v_exp_f32_e32 v79, v79
	v_add_f32_e32 v200, v200, v78
	v_add_f32_e32 v200, v200, v79
	v_cvt_pk_bf16_f32 v236, v64, v65
	v_cvt_pk_bf16_f32 v237, v66, v67
	v_cvt_pk_bf16_f32 v238, v68, v69
	v_cvt_pk_bf16_f32 v239, v70, v71
	v_cvt_pk_bf16_f32 v240, v72, v73
	v_cvt_pk_bf16_f32 v241, v74, v75
	v_cvt_pk_bf16_f32 v242, v76, v77
	v_cvt_pk_bf16_f32 v243, v78, v79
	v_mov_b32_e32 v68, v236
	v_mov_b32_e32 v69, v237
	v_mov_b32_e32 v70, v238
	v_mov_b32_e32 v71, v239
	v_mov_b32_e32 v64, v240
	v_mov_b32_e32 v65, v241
	v_mov_b32_e32 v66, v242
	v_mov_b32_e32 v67, v243
	s_branch .LBB0_1332
.Lat_idle0:
	s_cmp_lg_u32 s55, 0
	s_cbranch_scc1 .Lat_idle_go0
	s_mov_b32 s55, 1
	v_fma_f32 v64, v64, s84, -v199
	v_exp_f32_e32 v64, v64
	v_fma_f32 v65, v65, s84, -v199
	v_exp_f32_e32 v65, v65
	v_add_f32_e32 v200, v200, v64
	v_fma_f32 v66, v66, s84, -v199
	v_exp_f32_e32 v66, v66
	v_add_f32_e32 v200, v200, v65
	v_fma_f32 v67, v67, s84, -v199
	v_exp_f32_e32 v67, v67
	v_add_f32_e32 v200, v200, v66
	v_fma_f32 v68, v68, s84, -v199
	v_exp_f32_e32 v68, v68
	v_add_f32_e32 v200, v200, v67
	v_fma_f32 v69, v69, s84, -v199
	v_exp_f32_e32 v69, v69
	v_add_f32_e32 v200, v200, v68
	v_fma_f32 v70, v70, s84, -v199
	v_exp_f32_e32 v70, v70
	v_add_f32_e32 v200, v200, v69
	v_fma_f32 v71, v71, s84, -v199
	v_exp_f32_e32 v71, v71
	v_add_f32_e32 v200, v200, v70
	v_fma_f32 v72, v72, s84, -v199
	v_exp_f32_e32 v72, v72
	v_add_f32_e32 v200, v200, v71
	v_fma_f32 v73, v73, s84, -v199
	v_exp_f32_e32 v73, v73
	v_add_f32_e32 v200, v200, v72
	v_fma_f32 v74, v74, s84, -v199
	v_exp_f32_e32 v74, v74
	v_add_f32_e32 v200, v200, v73
	v_fma_f32 v75, v75, s84, -v199
	v_exp_f32_e32 v75, v75
	v_add_f32_e32 v200, v200, v74
	v_fma_f32 v76, v76, s84, -v199
	v_exp_f32_e32 v76, v76
	v_add_f32_e32 v200, v200, v75
	v_fma_f32 v77, v77, s84, -v199
	v_exp_f32_e32 v77, v77
	v_add_f32_e32 v200, v200, v76
	v_fma_f32 v78, v78, s84, -v199
	v_exp_f32_e32 v78, v78
	v_add_f32_e32 v200, v200, v77
	v_fma_f32 v79, v79, s84, -v199
	v_exp_f32_e32 v79, v79
	v_add_f32_e32 v200, v200, v78
	v_add_f32_e32 v200, v200, v79
	v_cvt_pk_bf16_f32 v64, v64, v65
	v_cvt_pk_bf16_f32 v65, v66, v67
	v_cvt_pk_bf16_f32 v66, v68, v69
	v_cvt_pk_bf16_f32 v67, v70, v71
	v_cvt_pk_bf16_f32 v68, v72, v73
	v_cvt_pk_bf16_f32 v69, v74, v75
	v_cvt_pk_bf16_f32 v70, v76, v77
	v_cvt_pk_bf16_f32 v71, v78, v79
	ds_read_b128 v[164:167], v144 offset:49152
	ds_read_b128 v[168:171], v144 offset:53248
	ds_read_b128 v[176:179], v144 offset:57344
	ds_read_b128 v[226:229], v144 offset:61440
	s_waitcnt lgkmcnt(0)
	v_mfma_f32_32x32x16_bf16 v[48:63], v[164:167], v[64:67], v[48:63]
	v_mfma_f32_32x32x16_bf16 v[32:47], v[168:171], v[64:67], v[32:47]
	v_mfma_f32_32x32x16_bf16 v[16:31], v[176:179], v[64:67], v[16:31]
	v_mfma_f32_32x32x16_bf16 v[0:15], v[226:229], v[64:67], v[0:15]
	ds_read_b128 v[164:167], v145 offset:49152
	ds_read_b128 v[168:171], v145 offset:53248
	ds_read_b128 v[176:179], v145 offset:57344
	ds_read_b128 v[226:229], v145 offset:61440
	s_waitcnt lgkmcnt(0)
	v_mfma_f32_32x32x16_bf16 v[48:63], v[164:167], v[68:71], v[48:63]
	v_mfma_f32_32x32x16_bf16 v[32:47], v[168:171], v[68:71], v[32:47]
	v_mfma_f32_32x32x16_bf16 v[16:31], v[176:179], v[68:71], v[16:31]
	v_mfma_f32_32x32x16_bf16 v[0:15], v[226:229], v[68:71], v[0:15]
	s_nop 7
	v_mov_b32_e32 v64, 0xff61b1e6
	v_mov_b32_e32 v65, v64
	v_mov_b32_e32 v66, v64
	v_mov_b32_e32 v67, v64
	v_mov_b32_e32 v68, v64
	v_mov_b32_e32 v69, v64
	v_mov_b32_e32 v70, v64
	v_mov_b32_e32 v71, v64
	v_mov_b32_e32 v72, v64
	v_mov_b32_e32 v73, v64
	v_mov_b32_e32 v74, v64
	v_mov_b32_e32 v75, v64
	v_mov_b32_e32 v76, v64
	v_mov_b32_e32 v77, v64
	v_mov_b32_e32 v78, v64
	v_mov_b32_e32 v79, v64

.Lat_resc_b0:
	ds_bpermute_b32 v175, v246, v172
	s_waitcnt lgkmcnt(0)
	v_max3_f32 v175, v199, v172, v175
	v_sub_f32_e32 v172, v199, v175
	v_exp_f32_e32 v172, v172
	v_mov_b32_e32 v199, v175
	s_nop 0
	v_mul_f32_e32 v200, v200, v172
	s_nop 15
	s_nop 3
	v_mul_f32_e32 v0, v172, v0
	v_mul_f32_e32 v1, v172, v1
	v_mul_f32_e32 v2, v172, v2
	v_mul_f32_e32 v3, v172, v3
	v_mul_f32_e32 v4, v172, v4
	v_mul_f32_e32 v5, v172, v5
	v_mul_f32_e32 v6, v172, v6
	v_mul_f32_e32 v7, v172, v7
	v_mul_f32_e32 v8, v172, v8
	v_mul_f32_e32 v9, v172, v9
	v_mul_f32_e32 v10, v172, v10
	v_mul_f32_e32 v11, v172, v11
	v_mul_f32_e32 v12, v172, v12
	v_mul_f32_e32 v13, v172, v13
	v_mul_f32_e32 v14, v172, v14
	v_mul_f32_e32 v15, v172, v15
	v_mul_f32_e32 v16, v172, v16
	v_mul_f32_e32 v17, v172, v17
	v_mul_f32_e32 v18, v172, v18
	v_mul_f32_e32 v19, v172, v19
	v_mul_f32_e32 v20, v172, v20
	v_mul_f32_e32 v21, v172, v21
	v_mul_f32_e32 v22, v172, v22
	v_mul_f32_e32 v23, v172, v23
	v_mul_f32_e32 v24, v172, v24
	v_mul_f32_e32 v25, v172, v25
	v_mul_f32_e32 v26, v172, v26
	v_mul_f32_e32 v27, v172, v27
	v_mul_f32_e32 v28, v172, v28
	v_mul_f32_e32 v29, v172, v29
	v_mul_f32_e32 v30, v172, v30
	v_mul_f32_e32 v31, v172, v31
	v_mul_f32_e32 v32, v172, v32
	v_mul_f32_e32 v33, v172, v33
	v_mul_f32_e32 v34, v172, v34
	v_mul_f32_e32 v35, v172, v35
	v_mul_f32_e32 v36, v172, v36
	v_mul_f32_e32 v37, v172, v37
	v_mul_f32_e32 v38, v172, v38
	v_mul_f32_e32 v39, v172, v39
	v_mul_f32_e32 v40, v172, v40
	v_mul_f32_e32 v41, v172, v41
	v_mul_f32_e32 v42, v172, v42
	v_mul_f32_e32 v43, v172, v43
	v_mul_f32_e32 v44, v172, v44
	v_mul_f32_e32 v45, v172, v45
	v_mul_f32_e32 v46, v172, v46
	v_mul_f32_e32 v47, v172, v47
	v_mul_f32_e32 v48, v172, v48
	v_mul_f32_e32 v49, v172, v49
	v_mul_f32_e32 v50, v172, v50
	v_mul_f32_e32 v51, v172, v51
	v_mul_f32_e32 v52, v172, v52
	v_mul_f32_e32 v53, v172, v53
	v_mul_f32_e32 v54, v172, v54
	v_mul_f32_e32 v55, v172, v55
	v_mul_f32_e32 v56, v172, v56
	v_mul_f32_e32 v57, v172, v57
	v_mul_f32_e32 v58, v172, v58
	v_mul_f32_e32 v59, v172, v59
	v_mul_f32_e32 v60, v172, v60
	v_mul_f32_e32 v61, v172, v61
	v_mul_f32_e32 v62, v172, v62
	v_mul_f32_e32 v63, v172, v63
	s_branch .Lat_resc_b0_ret
.Lat_idle1:
	s_cmp_lg_u32 s55, 0
	s_cbranch_scc1 .Lat_idle_go1
	s_mov_b32 s55, 1
	v_fma_f32 v64, v64, s84, -v199
	v_exp_f32_e32 v64, v64
	v_fma_f32 v65, v65, s84, -v199
	v_exp_f32_e32 v65, v65
	v_add_f32_e32 v200, v200, v64
	v_fma_f32 v66, v66, s84, -v199
	v_exp_f32_e32 v66, v66
	v_add_f32_e32 v200, v200, v65
	v_fma_f32 v67, v67, s84, -v199
	v_exp_f32_e32 v67, v67
	v_add_f32_e32 v200, v200, v66
	v_fma_f32 v68, v68, s84, -v199
	v_exp_f32_e32 v68, v68
	v_add_f32_e32 v200, v200, v67
	v_fma_f32 v69, v69, s84, -v199
	v_exp_f32_e32 v69, v69
	v_add_f32_e32 v200, v200, v68
	v_fma_f32 v70, v70, s84, -v199
	v_exp_f32_e32 v70, v70
	v_add_f32_e32 v200, v200, v69
	v_fma_f32 v71, v71, s84, -v199
	v_exp_f32_e32 v71, v71
	v_add_f32_e32 v200, v200, v70
	v_fma_f32 v72, v72, s84, -v199
	v_exp_f32_e32 v72, v72
	v_add_f32_e32 v200, v200, v71
	v_fma_f32 v73, v73, s84, -v199
	v_exp_f32_e32 v73, v73
	v_add_f32_e32 v200, v200, v72
	v_fma_f32 v74, v74, s84, -v199
	v_exp_f32_e32 v74, v74
	v_add_f32_e32 v200, v200, v73
	v_fma_f32 v75, v75, s84, -v199
	v_exp_f32_e32 v75, v75
	v_add_f32_e32 v200, v200, v74
	v_fma_f32 v76, v76, s84, -v199
	v_exp_f32_e32 v76, v76
	v_add_f32_e32 v200, v200, v75
	v_fma_f32 v77, v77, s84, -v199
	v_exp_f32_e32 v77, v77
	v_add_f32_e32 v200, v200, v76
	v_fma_f32 v78, v78, s84, -v199
	v_exp_f32_e32 v78, v78
	v_add_f32_e32 v200, v200, v77
	v_fma_f32 v79, v79, s84, -v199
	v_exp_f32_e32 v79, v79
	v_add_f32_e32 v200, v200, v78
	v_add_f32_e32 v200, v200, v79
	v_cvt_pk_bf16_f32 v64, v64, v65
	v_cvt_pk_bf16_f32 v65, v66, v67
	v_cvt_pk_bf16_f32 v66, v68, v69
	v_cvt_pk_bf16_f32 v67, v70, v71
	v_cvt_pk_bf16_f32 v68, v72, v73
	v_cvt_pk_bf16_f32 v69, v74, v75
	v_cvt_pk_bf16_f32 v70, v76, v77
	v_cvt_pk_bf16_f32 v71, v78, v79
	ds_read_b128 v[164:167], v144
	ds_read_b128 v[168:171], v144 offset:4096
	ds_read_b128 v[176:179], v144 offset:8192
	ds_read_b128 v[226:229], v144 offset:12288
	s_waitcnt lgkmcnt(0)
	v_mfma_f32_32x32x16_bf16 v[48:63], v[164:167], v[64:67], v[48:63]
	v_mfma_f32_32x32x16_bf16 v[32:47], v[168:171], v[64:67], v[32:47]
	v_mfma_f32_32x32x16_bf16 v[16:31], v[176:179], v[64:67], v[16:31]
	v_mfma_f32_32x32x16_bf16 v[0:15], v[226:229], v[64:67], v[0:15]
	ds_read_b128 v[164:167], v145
	ds_read_b128 v[168:171], v145 offset:4096
	ds_read_b128 v[176:179], v145 offset:8192
	ds_read_b128 v[226:229], v145 offset:12288
	s_waitcnt lgkmcnt(0)
	v_mfma_f32_32x32x16_bf16 v[48:63], v[164:167], v[68:71], v[48:63]
	v_mfma_f32_32x32x16_bf16 v[32:47], v[168:171], v[68:71], v[32:47]
	v_mfma_f32_32x32x16_bf16 v[16:31], v[176:179], v[68:71], v[16:31]
	v_mfma_f32_32x32x16_bf16 v[0:15], v[226:229], v[68:71], v[0:15]
	s_nop 7
	v_mov_b32_e32 v64, 0xff61b1e6
	v_mov_b32_e32 v65, v64
	v_mov_b32_e32 v66, v64
	v_mov_b32_e32 v67, v64
	v_mov_b32_e32 v68, v64
	v_mov_b32_e32 v69, v64
	v_mov_b32_e32 v70, v64
	v_mov_b32_e32 v71, v64
	v_mov_b32_e32 v72, v64
	v_mov_b32_e32 v73, v64
	v_mov_b32_e32 v74, v64
	v_mov_b32_e32 v75, v64
	v_mov_b32_e32 v76, v64
	v_mov_b32_e32 v77, v64
	v_mov_b32_e32 v78, v64
	v_mov_b32_e32 v79, v64

.Lat_idle2:
	s_cmp_lg_u32 s55, 0
	s_cbranch_scc1 .Lat_idle_go2
	s_mov_b32 s55, 1
	v_fma_f32 v64, v64, s84, -v199
	v_exp_f32_e32 v64, v64
	v_fma_f32 v65, v65, s84, -v199
	v_exp_f32_e32 v65, v65
	v_add_f32_e32 v200, v200, v64
	v_fma_f32 v66, v66, s84, -v199
	v_exp_f32_e32 v66, v66
	v_add_f32_e32 v200, v200, v65
	v_fma_f32 v67, v67, s84, -v199
	v_exp_f32_e32 v67, v67
	v_add_f32_e32 v200, v200, v66
	v_fma_f32 v68, v68, s84, -v199
	v_exp_f32_e32 v68, v68
	v_add_f32_e32 v200, v200, v67
	v_fma_f32 v69, v69, s84, -v199
	v_exp_f32_e32 v69, v69
	v_add_f32_e32 v200, v200, v68
	v_fma_f32 v70, v70, s84, -v199
	v_exp_f32_e32 v70, v70
	v_add_f32_e32 v200, v200, v69
	v_fma_f32 v71, v71, s84, -v199
	v_exp_f32_e32 v71, v71
	v_add_f32_e32 v200, v200, v70
	v_fma_f32 v72, v72, s84, -v199
	v_exp_f32_e32 v72, v72
	v_add_f32_e32 v200, v200, v71
	v_fma_f32 v73, v73, s84, -v199
	v_exp_f32_e32 v73, v73
	v_add_f32_e32 v200, v200, v72
	v_fma_f32 v74, v74, s84, -v199
	v_exp_f32_e32 v74, v74
	v_add_f32_e32 v200, v200, v73
	v_fma_f32 v75, v75, s84, -v199
	v_exp_f32_e32 v75, v75
	v_add_f32_e32 v200, v200, v74
	v_fma_f32 v76, v76, s84, -v199
	v_exp_f32_e32 v76, v76
	v_add_f32_e32 v200, v200, v75
	v_fma_f32 v77, v77, s84, -v199
	v_exp_f32_e32 v77, v77
	v_add_f32_e32 v200, v200, v76
	v_fma_f32 v78, v78, s84, -v199
	v_exp_f32_e32 v78, v78
	v_add_f32_e32 v200, v200, v77
	v_fma_f32 v79, v79, s84, -v199
	v_exp_f32_e32 v79, v79
	v_add_f32_e32 v200, v200, v78
	v_add_f32_e32 v200, v200, v79
	v_cvt_pk_bf16_f32 v64, v64, v65
	v_cvt_pk_bf16_f32 v65, v66, v67
	v_cvt_pk_bf16_f32 v66, v68, v69
	v_cvt_pk_bf16_f32 v67, v70, v71
	v_cvt_pk_bf16_f32 v68, v72, v73
	v_cvt_pk_bf16_f32 v69, v74, v75
	v_cvt_pk_bf16_f32 v70, v76, v77
	v_cvt_pk_bf16_f32 v71, v78, v79
	ds_read_b128 v[164:167], v144 offset:16384
	ds_read_b128 v[168:171], v144 offset:20480
	ds_read_b128 v[176:179], v144 offset:24576
	ds_read_b128 v[226:229], v144 offset:28672
	s_waitcnt lgkmcnt(0)
	v_mfma_f32_32x32x16_bf16 v[48:63], v[164:167], v[64:67], v[48:63]
	v_mfma_f32_32x32x16_bf16 v[32:47], v[168:171], v[64:67], v[32:47]
	v_mfma_f32_32x32x16_bf16 v[16:31], v[176:179], v[64:67], v[16:31]
	v_mfma_f32_32x32x16_bf16 v[0:15], v[226:229], v[64:67], v[0:15]
	ds_read_b128 v[164:167], v145 offset:16384
	ds_read_b128 v[168:171], v145 offset:20480
	ds_read_b128 v[176:179], v145 offset:24576
	ds_read_b128 v[226:229], v145 offset:28672
	s_waitcnt lgkmcnt(0)
	v_mfma_f32_32x32x16_bf16 v[48:63], v[164:167], v[68:71], v[48:63]
	v_mfma_f32_32x32x16_bf16 v[32:47], v[168:171], v[68:71], v[32:47]
	v_mfma_f32_32x32x16_bf16 v[16:31], v[176:179], v[68:71], v[16:31]
	v_mfma_f32_32x32x16_bf16 v[0:15], v[226:229], v[68:71], v[0:15]
	s_nop 7
	v_mov_b32_e32 v64, 0xff61b1e6
	v_mov_b32_e32 v65, v64
	v_mov_b32_e32 v66, v64
	v_mov_b32_e32 v67, v64
	v_mov_b32_e32 v68, v64
	v_mov_b32_e32 v69, v64
	v_mov_b32_e32 v70, v64
	v_mov_b32_e32 v71, v64
	v_mov_b32_e32 v72, v64
	v_mov_b32_e32 v73, v64
	v_mov_b32_e32 v74, v64
	v_mov_b32_e32 v75, v64
	v_mov_b32_e32 v76, v64
	v_mov_b32_e32 v77, v64
	v_mov_b32_e32 v78, v64
	v_mov_b32_e32 v79, v64

.Lat_idle3:
	s_cmp_lg_u32 s55, 0
	s_cbranch_scc1 .Lat_idle_go3
	s_mov_b32 s55, 1
	v_fma_f32 v64, v64, s84, -v199
	v_exp_f32_e32 v64, v64
	v_fma_f32 v65, v65, s84, -v199
	v_exp_f32_e32 v65, v65
	v_add_f32_e32 v200, v200, v64
	v_fma_f32 v66, v66, s84, -v199
	v_exp_f32_e32 v66, v66
	v_add_f32_e32 v200, v200, v65
	v_fma_f32 v67, v67, s84, -v199
	v_exp_f32_e32 v67, v67
	v_add_f32_e32 v200, v200, v66
	v_fma_f32 v68, v68, s84, -v199
	v_exp_f32_e32 v68, v68
	v_add_f32_e32 v200, v200, v67
	v_fma_f32 v69, v69, s84, -v199
	v_exp_f32_e32 v69, v69
	v_add_f32_e32 v200, v200, v68
	v_fma_f32 v70, v70, s84, -v199
	v_exp_f32_e32 v70, v70
	v_add_f32_e32 v200, v200, v69
	v_fma_f32 v71, v71, s84, -v199
	v_exp_f32_e32 v71, v71
	v_add_f32_e32 v200, v200, v70
	v_fma_f32 v72, v72, s84, -v199
	v_exp_f32_e32 v72, v72
	v_add_f32_e32 v200, v200, v71
	v_fma_f32 v73, v73, s84, -v199
	v_exp_f32_e32 v73, v73
	v_add_f32_e32 v200, v200, v72
	v_fma_f32 v74, v74, s84, -v199
	v_exp_f32_e32 v74, v74
	v_add_f32_e32 v200, v200, v73
	v_fma_f32 v75, v75, s84, -v199
	v_exp_f32_e32 v75, v75
	v_add_f32_e32 v200, v200, v74
	v_fma_f32 v76, v76, s84, -v199
	v_exp_f32_e32 v76, v76
	v_add_f32_e32 v200, v200, v75
	v_fma_f32 v77, v77, s84, -v199
	v_exp_f32_e32 v77, v77
	v_add_f32_e32 v200, v200, v76
	v_fma_f32 v78, v78, s84, -v199
	v_exp_f32_e32 v78, v78
	v_add_f32_e32 v200, v200, v77
	v_fma_f32 v79, v79, s84, -v199
	v_exp_f32_e32 v79, v79
	v_add_f32_e32 v200, v200, v78
	v_add_f32_e32 v200, v200, v79
	v_cvt_pk_bf16_f32 v64, v64, v65
	v_cvt_pk_bf16_f32 v65, v66, v67
	v_cvt_pk_bf16_f32 v66, v68, v69
	v_cvt_pk_bf16_f32 v67, v70, v71
	v_cvt_pk_bf16_f32 v68, v72, v73
	v_cvt_pk_bf16_f32 v69, v74, v75
	v_cvt_pk_bf16_f32 v70, v76, v77
	v_cvt_pk_bf16_f32 v71, v78, v79
	ds_read_b128 v[164:167], v144 offset:32768
	ds_read_b128 v[168:171], v144 offset:36864
	ds_read_b128 v[176:179], v144 offset:40960
	ds_read_b128 v[226:229], v144 offset:45056
	s_waitcnt lgkmcnt(0)
	v_mfma_f32_32x32x16_bf16 v[48:63], v[164:167], v[64:67], v[48:63]
	v_mfma_f32_32x32x16_bf16 v[32:47], v[168:171], v[64:67], v[32:47]
	v_mfma_f32_32x32x16_bf16 v[16:31], v[176:179], v[64:67], v[16:31]
	v_mfma_f32_32x32x16_bf16 v[0:15], v[226:229], v[64:67], v[0:15]
	ds_read_b128 v[164:167], v145 offset:32768
	ds_read_b128 v[168:171], v145 offset:36864
	ds_read_b128 v[176:179], v145 offset:40960
	ds_read_b128 v[226:229], v145 offset:45056
	s_waitcnt lgkmcnt(0)
	v_mfma_f32_32x32x16_bf16 v[48:63], v[164:167], v[68:71], v[48:63]
	v_mfma_f32_32x32x16_bf16 v[32:47], v[168:171], v[68:71], v[32:47]
	v_mfma_f32_32x32x16_bf16 v[16:31], v[176:179], v[68:71], v[16:31]
	v_mfma_f32_32x32x16_bf16 v[0:15], v[226:229], v[68:71], v[0:15]
	s_nop 7
	v_mov_b32_e32 v64, 0xff61b1e6
	v_mov_b32_e32 v65, v64
	v_mov_b32_e32 v66, v64
	v_mov_b32_e32 v67, v64
	v_mov_b32_e32 v68, v64
	v_mov_b32_e32 v69, v64
	v_mov_b32_e32 v70, v64
	v_mov_b32_e32 v71, v64
	v_mov_b32_e32 v72, v64
	v_mov_b32_e32 v73, v64
	v_mov_b32_e32 v74, v64
	v_mov_b32_e32 v75, v64
	v_mov_b32_e32 v76, v64
	v_mov_b32_e32 v77, v64
	v_mov_b32_e32 v78, v64
	v_mov_b32_e32 v79, v64
